# proj epilogue: batch LDS reads and gamma/rope global loads for all 5 segment branches
# speedup vs baseline: 1.0108x; 1.0047x over previous
.LBB0_453:
	v_add_u32_e32 v0, 0x400, v152
	ds_write2_b32 v152, v50, v34 offset1:32
	ds_write2_b32 v152, v51, v35 offset0:129 offset1:161
	ds_write2_b32 v0, v52, v36 offset0:2 offset1:34
	ds_write2_b32 v0, v53, v37 offset0:131 offset1:163
	v_add_u32_e32 v0, 0x1000, v152
	ds_write2_b32 v0, v54, v38 offset0:8 offset1:40
	ds_write2_b32 v0, v55, v39 offset0:137 offset1:169
	v_add_u32_e32 v0, 0x1400, v152
	ds_write2_b32 v0, v56, v40 offset0:10 offset1:42
	ds_write2_b32 v0, v57, v41 offset0:139 offset1:171
	v_add_u32_e32 v0, 0x2000, v152
	ds_write2_b32 v0, v58, v42 offset0:16 offset1:48
	ds_write2_b32 v0, v59, v43 offset0:145 offset1:177
	v_add_u32_e32 v0, 0x2400, v152
	ds_write2_b32 v0, v60, v44 offset0:18 offset1:50
	ds_write2_b32 v0, v61, v45 offset0:147 offset1:179
	v_add_u32_e32 v0, 0x3000, v152
	ds_write2_b32 v0, v62, v46 offset0:24 offset1:56
	ds_write2_b32 v0, v63, v47 offset0:153 offset1:185
	v_add_u32_e32 v0, 0x3400, v152
	ds_write2_b32 v0, v64, v48 offset0:26 offset1:58
	ds_write2_b32 v0, v65, v49 offset0:155 offset1:187
	v_add_u32_e32 v0, 0x4000, v152
	ds_write2_b32 v0, v18, v2 offset0:32 offset1:64
	ds_write2_b32 v0, v19, v3 offset0:161 offset1:193
	v_add_u32_e32 v0, 0x4400, v152
	ds_write2_b32 v0, v20, v4 offset0:34 offset1:66
	ds_write2_b32 v0, v21, v5 offset0:163 offset1:195
	v_add_u32_e32 v0, 0x5000, v152
	ds_write2_b32 v0, v22, v6 offset0:40 offset1:72
	ds_write2_b32 v0, v23, v7 offset0:169 offset1:201
	v_add_u32_e32 v0, 0x5400, v152
	ds_write2_b32 v0, v24, v8 offset0:42 offset1:74
	ds_write2_b32 v0, v25, v9 offset0:171 offset1:203
	v_add_u32_e32 v0, 0x6000, v152
	ds_write2_b32 v0, v26, v10 offset0:48 offset1:80
	ds_write2_b32 v0, v27, v11 offset0:177 offset1:209
	v_add_u32_e32 v0, 0x6400, v152
	v_add_u32_e32 v24, s10, v135
	s_movk_i32 s8, 0x2000
	ds_write2_b32 v0, v28, v12 offset0:50 offset1:82
	ds_write2_b32 v0, v29, v13 offset0:179 offset1:211
	v_add_u32_e32 v0, 0x7000, v152
	v_cmp_gt_i32_e64 s[40:41], s8, v24
	s_movk_i32 s8, 0x1fff
	ds_write2_b32 v0, v30, v14 offset0:56 offset1:88
	ds_write2_b32 v0, v31, v15 offset0:185 offset1:217
	v_add_u32_e32 v0, 0x7400, v152
	v_cmp_lt_i32_e64 s[42:43], s8, v24
	ds_write2_b32 v0, v32, v16 offset0:58 offset1:90
	ds_write2_b32 v0, v33, v17 offset0:187 offset1:219
	s_waitcnt lgkmcnt(0)
	s_barrier
	s_and_saveexec_b64 s[8:9], s[42:43]
	s_xor_b64 s[8:9], exec, s[8:9]
	v_add_u32_e32 v0, 0xffffe000, v24
	v_lshrrev_b32_e32 v26, 12, v0
	s_or_saveexec_b64 s[8:9], s[8:9]
	v_mov_b64_e32 v[28:29], 0x1000
	v_mov_b64_e32 v[30:31], 0x200000
	v_mov_b32_e32 v10, 0xfff
	s_xor_b64 exec, exec, s[8:9]
	v_ashrrev_i32_e32 v26, 8, v24
	v_mov_b64_e32 v[28:29], 0x100
	v_mov_b64_e32 v[30:31], 0
	v_mov_b32_e32 v10, 0xff
	s_or_b64 exec, exec, s[8:9]
	s_ashr_i32 s19, s12, 1
	s_and_b32 s16, s12, 1
	s_cmp_lt_u32 s12, 2
	s_cselect_b64 s[8:9], -1, 0
	s_cmp_gt_u32 s12, 1
	s_cselect_b64 s[10:11], -1, 0
	s_cmp_lg_u32 s19, 1
	s_cselect_b64 s[14:15], -1, 0
	s_and_b64 s[14:15], s[10:11], s[14:15]
	v_lshl_or_b32 v156, s16, 7, v154
	s_mov_b64 s[10:11], -1
	s_and_b64 vcc, exec, s[14:15]
	s_cbranch_vccz .LBB0_467
	s_and_b32 s17, s12, -4
	s_mov_b64 s[14:15], -1
	s_mov_b64 s[10:11], 0
	s_cmp_lt_i32 s17, 16
	s_mov_b64 s[12:13], 0
	s_cbranch_scc1 .LBB0_462
	s_cmp_eq_u32 s17, 16
	s_mov_b64 s[12:13], -1
	s_cbranch_scc0 .LBB0_461
	s_cmp_eq_u32 s19, 8
	s_mov_b32 s12, 0xf885100
	ds_read2_b32 v[4:5], v155 offset1:1
	ds_read2_b32 v[36:37], v155 offset0:2 offset1:3
	ds_read2_b32 v[38:39], v155 offset0:4 offset1:5
	ds_read2_b32 v[40:41], v155 offset0:6 offset1:7
	ds_read2_b32 v[42:43], v155 offset0:8 offset1:9
	ds_read2_b32 v[44:45], v155 offset0:10 offset1:11
	ds_read2_b32 v[46:47], v155 offset0:12 offset1:13
	ds_read2_b32 v[48:49], v155 offset0:14 offset1:15
	ds_read2_b32 v[50:51], v155 offset0:16 offset1:17
	ds_read2_b32 v[52:53], v155 offset0:18 offset1:19
	ds_read2_b32 v[54:55], v155 offset0:20 offset1:21
	ds_read2_b32 v[56:57], v155 offset0:22 offset1:23
	ds_read2_b32 v[58:59], v155 offset0:24 offset1:25
	ds_read2_b32 v[60:61], v155 offset0:26 offset1:27
	ds_read2_b32 v[62:63], v155 offset0:28 offset1:29
	ds_read2_b32 v[64:65], v155 offset0:30 offset1:31
	ds_read2_b32 v[98:99], v155 offset0:32 offset1:33
	ds_read2_b32 v[100:101], v155 offset0:34 offset1:35
	ds_read2_b32 v[102:103], v155 offset0:36 offset1:37
	ds_read2_b32 v[104:105], v155 offset0:38 offset1:39
	ds_read2_b32 v[106:107], v155 offset0:40 offset1:41
	ds_read2_b32 v[108:109], v155 offset0:42 offset1:43
	ds_read2_b32 v[110:111], v155 offset0:44 offset1:45
	ds_read2_b32 v[112:113], v155 offset0:46 offset1:47
	ds_read2_b32 v[114:115], v155 offset0:48 offset1:49
	ds_read2_b32 v[116:117], v155 offset0:50 offset1:51
	ds_read2_b32 v[118:119], v155 offset0:52 offset1:53
	ds_read2_b32 v[120:121], v155 offset0:54 offset1:55
	ds_read2_b32 v[122:123], v155 offset0:56 offset1:57
	ds_read2_b32 v[124:125], v155 offset0:58 offset1:59
	ds_read2_b32 v[126:127], v155 offset0:60 offset1:61
	ds_read2_b32 v[128:129], v155 offset0:62 offset1:63
	s_cselect_b32 s12, s12, 0x10085100
	s_add_u32 s12, s94, s12
	v_ashrrev_i32_e32 v25, 31, v24
	s_addc_u32 s13, s95, 0
	v_lshlrev_b64 v[2:3], 9, v[24:25]
	v_lshl_add_u64 v[2:3], s[12:13], 0, v[2:3]
	v_lshlrev_b32_e32 v0, 1, v156
	v_lshl_add_u64 v[2:3], v[2:3], 0, v[0:1]
	s_waitcnt lgkmcnt(0)
	v_mul_f32_e32 v0, 0x3d372713, v4
	v_mul_f32_e32 v0, v4, v0
	v_fma_f32 v0, v4, v0, v4
	v_mul_f32_e32 v0, 0x3f4c422a, v0
	v_add_f32_e32 v0, v0, v0
	v_mul_f32_e32 v0, 0x3fb8aa3b, v0
	v_exp_f32_e32 v0, v0
	s_mov_b64 s[12:13], 0
	v_add_f32_e32 v0, 1.0, v0
	v_rcp_f32_e32 v6, v0
	v_mul_f32_e32 v0, 0x3d372713, v5
	v_mul_f32_e32 v0, v5, v0
	v_fma_f32 v0, v5, v0, v5
	v_mul_f32_e32 v0, 0x3f4c422a, v0
	v_add_f32_e32 v0, v0, v0
	v_mul_f32_e32 v0, 0x3fb8aa3b, v0
	v_exp_f32_e32 v0, v0
	v_pk_mul_f32 v[4:5], v[4:5], 0.5 op_sel_hi:[1,0]
	v_add_f32_e32 v0, 1.0, v0
	v_rcp_f32_e32 v7, v0
	s_nop 0
	v_pk_fma_f32 v[6:7], v[6:7], 2.0, 1.0 op_sel_hi:[1,0,0] neg_lo:[1,0,0] neg_hi:[1,0,0]
	s_nop 0
	v_pk_add_f32 v[6:7], v[6:7], 1.0 op_sel_hi:[1,0]
	s_nop 0
	v_pk_mul_f32 v[4:5], v[4:5], v[6:7]
	v_mov_b64_e32 v[6:7], v[36:37]
	v_cvt_pk_bf16_f32 v4, v4, v5
	s_waitcnt lgkmcnt(0)
	v_mul_f32_e32 v0, 0x3d372713, v6
	v_mul_f32_e32 v0, v6, v0
	v_fma_f32 v0, v6, v0, v6
	v_mul_f32_e32 v0, 0x3f4c422a, v0
	v_add_f32_e32 v0, v0, v0
	v_mul_f32_e32 v0, 0x3fb8aa3b, v0
	v_exp_f32_e32 v0, v0
	s_nop 0
	v_add_f32_e32 v0, 1.0, v0
	v_rcp_f32_e32 v8, v0
	v_mul_f32_e32 v0, 0x3d372713, v7
	v_mul_f32_e32 v0, v7, v0
	v_fma_f32 v0, v7, v0, v7
	v_mul_f32_e32 v0, 0x3f4c422a, v0
	v_add_f32_e32 v0, v0, v0
	v_mul_f32_e32 v0, 0x3fb8aa3b, v0
	v_exp_f32_e32 v0, v0
	v_pk_mul_f32 v[6:7], v[6:7], 0.5 op_sel_hi:[1,0]
	v_add_f32_e32 v0, 1.0, v0
	v_rcp_f32_e32 v9, v0
	s_nop 0
	v_pk_fma_f32 v[8:9], v[8:9], 2.0, 1.0 op_sel_hi:[1,0,0] neg_lo:[1,0,0] neg_hi:[1,0,0]
	s_nop 0
	v_pk_add_f32 v[8:9], v[8:9], 1.0 op_sel_hi:[1,0]
	s_nop 0
	v_pk_mul_f32 v[6:7], v[6:7], v[8:9]
	v_mov_b64_e32 v[8:9], v[38:39]
	v_cvt_pk_bf16_f32 v5, v6, v7
	s_waitcnt lgkmcnt(0)
	v_mul_f32_e32 v0, 0x3d372713, v8
	v_mul_f32_e32 v0, v8, v0
	v_fma_f32 v0, v8, v0, v8
	v_mul_f32_e32 v0, 0x3f4c422a, v0
	v_add_f32_e32 v0, v0, v0
	v_mul_f32_e32 v0, 0x3fb8aa3b, v0
	v_exp_f32_e32 v0, v0
	s_nop 0
	v_add_f32_e32 v0, 1.0, v0
	v_rcp_f32_e32 v12, v0
	v_mul_f32_e32 v0, 0x3d372713, v9
	v_mul_f32_e32 v0, v9, v0
	v_fma_f32 v0, v9, v0, v9
	v_mul_f32_e32 v0, 0x3f4c422a, v0
	v_add_f32_e32 v0, v0, v0
	v_mul_f32_e32 v0, 0x3fb8aa3b, v0
	v_exp_f32_e32 v0, v0
	v_pk_mul_f32 v[8:9], v[8:9], 0.5 op_sel_hi:[1,0]
	v_add_f32_e32 v0, 1.0, v0
	v_rcp_f32_e32 v13, v0
	s_nop 0
	v_pk_fma_f32 v[12:13], v[12:13], 2.0, 1.0 op_sel_hi:[1,0,0] neg_lo:[1,0,0] neg_hi:[1,0,0]
	s_nop 0
	v_pk_add_f32 v[12:13], v[12:13], 1.0 op_sel_hi:[1,0]
	s_nop 0
	v_pk_mul_f32 v[8:9], v[8:9], v[12:13]
	v_mov_b64_e32 v[12:13], v[40:41]
	v_cvt_pk_bf16_f32 v6, v8, v9
	s_waitcnt lgkmcnt(0)
	v_mul_f32_e32 v0, 0x3d372713, v12
	v_mul_f32_e32 v0, v12, v0
	v_fma_f32 v0, v12, v0, v12
	v_mul_f32_e32 v0, 0x3f4c422a, v0
	v_add_f32_e32 v0, v0, v0
	v_mul_f32_e32 v0, 0x3fb8aa3b, v0
	v_exp_f32_e32 v0, v0
	s_nop 0
	v_add_f32_e32 v0, 1.0, v0
	v_rcp_f32_e32 v14, v0
	v_mul_f32_e32 v0, 0x3d372713, v13
	v_mul_f32_e32 v0, v13, v0
	v_fma_f32 v0, v13, v0, v13
	v_mul_f32_e32 v0, 0x3f4c422a, v0
	v_add_f32_e32 v0, v0, v0
	v_mul_f32_e32 v0, 0x3fb8aa3b, v0
	v_exp_f32_e32 v0, v0
	v_pk_mul_f32 v[12:13], v[12:13], 0.5 op_sel_hi:[1,0]
	v_add_f32_e32 v0, 1.0, v0
	v_rcp_f32_e32 v15, v0
	s_nop 0
	v_pk_fma_f32 v[14:15], v[14:15], 2.0, 1.0 op_sel_hi:[1,0,0] neg_lo:[1,0,0] neg_hi:[1,0,0]
	s_nop 0
	v_pk_add_f32 v[14:15], v[14:15], 1.0 op_sel_hi:[1,0]
	s_nop 0
	v_pk_mul_f32 v[12:13], v[12:13], v[14:15]
	s_nop 0
	v_cvt_pk_bf16_f32 v7, v12, v13
	global_store_dwordx4 v[2:3], v[4:7], off
	s_nop 1
	v_mov_b64_e32 v[4:5], v[42:43]
	s_waitcnt lgkmcnt(0)
	v_mul_f32_e32 v0, 0x3d372713, v4
	v_mul_f32_e32 v0, v4, v0
	v_fma_f32 v0, v4, v0, v4
	v_mul_f32_e32 v0, 0x3f4c422a, v0
	v_add_f32_e32 v0, v0, v0
	v_mul_f32_e32 v0, 0x3fb8aa3b, v0
	v_exp_f32_e32 v0, v0
	s_nop 0
	v_add_f32_e32 v0, 1.0, v0
	v_rcp_f32_e32 v6, v0
	v_mul_f32_e32 v0, 0x3d372713, v5
	v_mul_f32_e32 v0, v5, v0
	v_fma_f32 v0, v5, v0, v5
	v_mul_f32_e32 v0, 0x3f4c422a, v0
	v_add_f32_e32 v0, v0, v0
	v_mul_f32_e32 v0, 0x3fb8aa3b, v0
	v_exp_f32_e32 v0, v0
	v_pk_mul_f32 v[4:5], v[4:5], 0.5 op_sel_hi:[1,0]
	v_add_f32_e32 v0, 1.0, v0
	v_rcp_f32_e32 v7, v0
	s_nop 0
	v_pk_fma_f32 v[6:7], v[6:7], 2.0, 1.0 op_sel_hi:[1,0,0] neg_lo:[1,0,0] neg_hi:[1,0,0]
	s_nop 0
	v_pk_add_f32 v[6:7], v[6:7], 1.0 op_sel_hi:[1,0]
	s_nop 0
	v_pk_mul_f32 v[4:5], v[4:5], v[6:7]
	v_mov_b64_e32 v[6:7], v[44:45]
	v_cvt_pk_bf16_f32 v4, v4, v5
	s_waitcnt lgkmcnt(0)
	v_mul_f32_e32 v0, 0x3d372713, v6
	v_mul_f32_e32 v0, v6, v0
	v_fma_f32 v0, v6, v0, v6
	v_mul_f32_e32 v0, 0x3f4c422a, v0
	v_add_f32_e32 v0, v0, v0
	v_mul_f32_e32 v0, 0x3fb8aa3b, v0
	v_exp_f32_e32 v0, v0
	s_nop 0
	v_add_f32_e32 v0, 1.0, v0
	v_rcp_f32_e32 v8, v0
	v_mul_f32_e32 v0, 0x3d372713, v7
	v_mul_f32_e32 v0, v7, v0
	v_fma_f32 v0, v7, v0, v7
	v_mul_f32_e32 v0, 0x3f4c422a, v0
	v_add_f32_e32 v0, v0, v0
	v_mul_f32_e32 v0, 0x3fb8aa3b, v0
	v_exp_f32_e32 v0, v0
	v_pk_mul_f32 v[6:7], v[6:7], 0.5 op_sel_hi:[1,0]
	v_add_f32_e32 v0, 1.0, v0
	v_rcp_f32_e32 v9, v0
	s_nop 0
	v_pk_fma_f32 v[8:9], v[8:9], 2.0, 1.0 op_sel_hi:[1,0,0] neg_lo:[1,0,0] neg_hi:[1,0,0]
	s_nop 0
	v_pk_add_f32 v[8:9], v[8:9], 1.0 op_sel_hi:[1,0]
	s_nop 0
	v_pk_mul_f32 v[6:7], v[6:7], v[8:9]
	v_mov_b64_e32 v[8:9], v[46:47]
	v_cvt_pk_bf16_f32 v5, v6, v7
	s_waitcnt lgkmcnt(0)
	v_mul_f32_e32 v0, 0x3d372713, v8
	v_mul_f32_e32 v0, v8, v0
	v_fma_f32 v0, v8, v0, v8
	v_mul_f32_e32 v0, 0x3f4c422a, v0
	v_add_f32_e32 v0, v0, v0
	v_mul_f32_e32 v0, 0x3fb8aa3b, v0
	v_exp_f32_e32 v0, v0
	s_nop 0
	v_add_f32_e32 v0, 1.0, v0
	v_rcp_f32_e32 v12, v0
	v_mul_f32_e32 v0, 0x3d372713, v9
	v_mul_f32_e32 v0, v9, v0
	v_fma_f32 v0, v9, v0, v9
	v_mul_f32_e32 v0, 0x3f4c422a, v0
	v_add_f32_e32 v0, v0, v0
	v_mul_f32_e32 v0, 0x3fb8aa3b, v0
	v_exp_f32_e32 v0, v0
	v_pk_mul_f32 v[8:9], v[8:9], 0.5 op_sel_hi:[1,0]
	v_add_f32_e32 v0, 1.0, v0
	v_rcp_f32_e32 v13, v0
	s_nop 0
	v_pk_fma_f32 v[12:13], v[12:13], 2.0, 1.0 op_sel_hi:[1,0,0] neg_lo:[1,0,0] neg_hi:[1,0,0]
	s_nop 0
	v_pk_add_f32 v[12:13], v[12:13], 1.0 op_sel_hi:[1,0]
	s_nop 0
	v_pk_mul_f32 v[8:9], v[8:9], v[12:13]
	v_mov_b64_e32 v[12:13], v[48:49]
	v_cvt_pk_bf16_f32 v6, v8, v9
	s_waitcnt lgkmcnt(0)
	v_mul_f32_e32 v0, 0x3d372713, v12
	v_mul_f32_e32 v0, v12, v0
	v_fma_f32 v0, v12, v0, v12
	v_mul_f32_e32 v0, 0x3f4c422a, v0
	v_add_f32_e32 v0, v0, v0
	v_mul_f32_e32 v0, 0x3fb8aa3b, v0
	v_exp_f32_e32 v0, v0
	s_nop 0
	v_add_f32_e32 v0, 1.0, v0
	v_rcp_f32_e32 v14, v0
	v_mul_f32_e32 v0, 0x3d372713, v13
	v_mul_f32_e32 v0, v13, v0
	v_fma_f32 v0, v13, v0, v13
	v_mul_f32_e32 v0, 0x3f4c422a, v0
	v_add_f32_e32 v0, v0, v0
	v_mul_f32_e32 v0, 0x3fb8aa3b, v0
	v_exp_f32_e32 v0, v0
	v_pk_mul_f32 v[12:13], v[12:13], 0.5 op_sel_hi:[1,0]
	v_add_f32_e32 v0, 1.0, v0
	v_rcp_f32_e32 v15, v0
	s_nop 0
	v_pk_fma_f32 v[14:15], v[14:15], 2.0, 1.0 op_sel_hi:[1,0,0] neg_lo:[1,0,0] neg_hi:[1,0,0]
	s_nop 0
	v_pk_add_f32 v[14:15], v[14:15], 1.0 op_sel_hi:[1,0]
	s_nop 0
	v_pk_mul_f32 v[12:13], v[12:13], v[14:15]
	s_nop 0
	v_cvt_pk_bf16_f32 v7, v12, v13
	global_store_dwordx4 v[2:3], v[4:7], off offset:16
	s_nop 1
	v_mov_b64_e32 v[4:5], v[50:51]
	s_waitcnt lgkmcnt(0)
	v_mul_f32_e32 v0, 0x3d372713, v4
	v_mul_f32_e32 v0, v4, v0
	v_fma_f32 v0, v4, v0, v4
	v_mul_f32_e32 v0, 0x3f4c422a, v0
	v_add_f32_e32 v0, v0, v0
	v_mul_f32_e32 v0, 0x3fb8aa3b, v0
	v_exp_f32_e32 v0, v0
	s_nop 0
	v_add_f32_e32 v0, 1.0, v0
	v_rcp_f32_e32 v6, v0
	v_mul_f32_e32 v0, 0x3d372713, v5
	v_mul_f32_e32 v0, v5, v0
	v_fma_f32 v0, v5, v0, v5
	v_mul_f32_e32 v0, 0x3f4c422a, v0
	v_add_f32_e32 v0, v0, v0
	v_mul_f32_e32 v0, 0x3fb8aa3b, v0
	v_exp_f32_e32 v0, v0
	v_pk_mul_f32 v[4:5], v[4:5], 0.5 op_sel_hi:[1,0]
	v_add_f32_e32 v0, 1.0, v0
	v_rcp_f32_e32 v7, v0
	s_nop 0
	v_pk_fma_f32 v[6:7], v[6:7], 2.0, 1.0 op_sel_hi:[1,0,0] neg_lo:[1,0,0] neg_hi:[1,0,0]
	s_nop 0
	v_pk_add_f32 v[6:7], v[6:7], 1.0 op_sel_hi:[1,0]
	s_nop 0
	v_pk_mul_f32 v[4:5], v[4:5], v[6:7]
	v_mov_b64_e32 v[6:7], v[52:53]
	v_cvt_pk_bf16_f32 v4, v4, v5
	s_waitcnt lgkmcnt(0)
	v_mul_f32_e32 v0, 0x3d372713, v6
	v_mul_f32_e32 v0, v6, v0
	v_fma_f32 v0, v6, v0, v6
	v_mul_f32_e32 v0, 0x3f4c422a, v0
	v_add_f32_e32 v0, v0, v0
	v_mul_f32_e32 v0, 0x3fb8aa3b, v0
	v_exp_f32_e32 v0, v0
	s_nop 0
	v_add_f32_e32 v0, 1.0, v0
	v_rcp_f32_e32 v8, v0
	v_mul_f32_e32 v0, 0x3d372713, v7
	v_mul_f32_e32 v0, v7, v0
	v_fma_f32 v0, v7, v0, v7
	v_mul_f32_e32 v0, 0x3f4c422a, v0
	v_add_f32_e32 v0, v0, v0
	v_mul_f32_e32 v0, 0x3fb8aa3b, v0
	v_exp_f32_e32 v0, v0
	v_pk_mul_f32 v[6:7], v[6:7], 0.5 op_sel_hi:[1,0]
	v_add_f32_e32 v0, 1.0, v0
	v_rcp_f32_e32 v9, v0
	s_nop 0
	v_pk_fma_f32 v[8:9], v[8:9], 2.0, 1.0 op_sel_hi:[1,0,0] neg_lo:[1,0,0] neg_hi:[1,0,0]
	s_nop 0
	v_pk_add_f32 v[8:9], v[8:9], 1.0 op_sel_hi:[1,0]
	s_nop 0
	v_pk_mul_f32 v[6:7], v[6:7], v[8:9]
	v_mov_b64_e32 v[8:9], v[54:55]
	v_cvt_pk_bf16_f32 v5, v6, v7
	s_waitcnt lgkmcnt(0)
	v_mul_f32_e32 v0, 0x3d372713, v8
	v_mul_f32_e32 v0, v8, v0
	v_fma_f32 v0, v8, v0, v8
	v_mul_f32_e32 v0, 0x3f4c422a, v0
	v_add_f32_e32 v0, v0, v0
	v_mul_f32_e32 v0, 0x3fb8aa3b, v0
	v_exp_f32_e32 v0, v0
	s_nop 0
	v_add_f32_e32 v0, 1.0, v0
	v_rcp_f32_e32 v12, v0
	v_mul_f32_e32 v0, 0x3d372713, v9
	v_mul_f32_e32 v0, v9, v0
	v_fma_f32 v0, v9, v0, v9
	v_mul_f32_e32 v0, 0x3f4c422a, v0
	v_add_f32_e32 v0, v0, v0
	v_mul_f32_e32 v0, 0x3fb8aa3b, v0
	v_exp_f32_e32 v0, v0
	v_pk_mul_f32 v[8:9], v[8:9], 0.5 op_sel_hi:[1,0]
	v_add_f32_e32 v0, 1.0, v0
	v_rcp_f32_e32 v13, v0
	s_nop 0
	v_pk_fma_f32 v[12:13], v[12:13], 2.0, 1.0 op_sel_hi:[1,0,0] neg_lo:[1,0,0] neg_hi:[1,0,0]
	s_nop 0
	v_pk_add_f32 v[12:13], v[12:13], 1.0 op_sel_hi:[1,0]
	s_nop 0
	v_pk_mul_f32 v[8:9], v[8:9], v[12:13]
	v_mov_b64_e32 v[12:13], v[56:57]
	v_cvt_pk_bf16_f32 v6, v8, v9
	s_waitcnt lgkmcnt(0)
	v_mul_f32_e32 v0, 0x3d372713, v12
	v_mul_f32_e32 v0, v12, v0
	v_fma_f32 v0, v12, v0, v12
	v_mul_f32_e32 v0, 0x3f4c422a, v0
	v_add_f32_e32 v0, v0, v0
	v_mul_f32_e32 v0, 0x3fb8aa3b, v0
	v_exp_f32_e32 v0, v0
	s_nop 0
	v_add_f32_e32 v0, 1.0, v0
	v_rcp_f32_e32 v14, v0
	v_mul_f32_e32 v0, 0x3d372713, v13
	v_mul_f32_e32 v0, v13, v0
	v_fma_f32 v0, v13, v0, v13
	v_mul_f32_e32 v0, 0x3f4c422a, v0
	v_add_f32_e32 v0, v0, v0
	v_mul_f32_e32 v0, 0x3fb8aa3b, v0
	v_exp_f32_e32 v0, v0
	v_pk_mul_f32 v[12:13], v[12:13], 0.5 op_sel_hi:[1,0]
	v_add_f32_e32 v0, 1.0, v0
	v_rcp_f32_e32 v15, v0
	s_nop 0
	v_pk_fma_f32 v[14:15], v[14:15], 2.0, 1.0 op_sel_hi:[1,0,0] neg_lo:[1,0,0] neg_hi:[1,0,0]
	s_nop 0
	v_pk_add_f32 v[14:15], v[14:15], 1.0 op_sel_hi:[1,0]
	s_nop 0
	v_pk_mul_f32 v[12:13], v[12:13], v[14:15]
	s_nop 0
	v_cvt_pk_bf16_f32 v7, v12, v13
	global_store_dwordx4 v[2:3], v[4:7], off offset:32
	s_nop 1
	v_mov_b64_e32 v[4:5], v[58:59]
	s_waitcnt lgkmcnt(0)
	v_mul_f32_e32 v0, 0x3d372713, v4
	v_mul_f32_e32 v0, v4, v0
	v_fma_f32 v0, v4, v0, v4
	v_mul_f32_e32 v0, 0x3f4c422a, v0
	v_add_f32_e32 v0, v0, v0
	v_mul_f32_e32 v0, 0x3fb8aa3b, v0
	v_exp_f32_e32 v0, v0
	s_nop 0
	v_add_f32_e32 v0, 1.0, v0
	v_rcp_f32_e32 v6, v0
	v_mul_f32_e32 v0, 0x3d372713, v5
	v_mul_f32_e32 v0, v5, v0
	v_fma_f32 v0, v5, v0, v5
	v_mul_f32_e32 v0, 0x3f4c422a, v0
	v_add_f32_e32 v0, v0, v0
	v_mul_f32_e32 v0, 0x3fb8aa3b, v0
	v_exp_f32_e32 v0, v0
	v_pk_mul_f32 v[4:5], v[4:5], 0.5 op_sel_hi:[1,0]
	v_add_f32_e32 v0, 1.0, v0
	v_rcp_f32_e32 v7, v0
	s_nop 0
	v_pk_fma_f32 v[6:7], v[6:7], 2.0, 1.0 op_sel_hi:[1,0,0] neg_lo:[1,0,0] neg_hi:[1,0,0]
	s_nop 0
	v_pk_add_f32 v[6:7], v[6:7], 1.0 op_sel_hi:[1,0]
	s_nop 0
	v_pk_mul_f32 v[4:5], v[4:5], v[6:7]
	v_mov_b64_e32 v[6:7], v[60:61]
	v_cvt_pk_bf16_f32 v4, v4, v5
	s_waitcnt lgkmcnt(0)
	v_mul_f32_e32 v0, 0x3d372713, v6
	v_mul_f32_e32 v0, v6, v0
	v_fma_f32 v0, v6, v0, v6
	v_mul_f32_e32 v0, 0x3f4c422a, v0
	v_add_f32_e32 v0, v0, v0
	v_mul_f32_e32 v0, 0x3fb8aa3b, v0
	v_exp_f32_e32 v0, v0
	s_nop 0
	v_add_f32_e32 v0, 1.0, v0
	v_rcp_f32_e32 v8, v0
	v_mul_f32_e32 v0, 0x3d372713, v7
	v_mul_f32_e32 v0, v7, v0
	v_fma_f32 v0, v7, v0, v7
	v_mul_f32_e32 v0, 0x3f4c422a, v0
	v_add_f32_e32 v0, v0, v0
	v_mul_f32_e32 v0, 0x3fb8aa3b, v0
	v_exp_f32_e32 v0, v0
	v_pk_mul_f32 v[6:7], v[6:7], 0.5 op_sel_hi:[1,0]
	v_add_f32_e32 v0, 1.0, v0
	v_rcp_f32_e32 v9, v0
	s_nop 0
	v_pk_fma_f32 v[8:9], v[8:9], 2.0, 1.0 op_sel_hi:[1,0,0] neg_lo:[1,0,0] neg_hi:[1,0,0]
	s_nop 0
	v_pk_add_f32 v[8:9], v[8:9], 1.0 op_sel_hi:[1,0]
	s_nop 0
	v_pk_mul_f32 v[6:7], v[6:7], v[8:9]
	v_mov_b64_e32 v[8:9], v[62:63]
	v_cvt_pk_bf16_f32 v5, v6, v7
	s_waitcnt lgkmcnt(0)
	v_mul_f32_e32 v0, 0x3d372713, v8
	v_mul_f32_e32 v0, v8, v0
	v_fma_f32 v0, v8, v0, v8
	v_mul_f32_e32 v0, 0x3f4c422a, v0
	v_add_f32_e32 v0, v0, v0
	v_mul_f32_e32 v0, 0x3fb8aa3b, v0
	v_exp_f32_e32 v0, v0
	s_nop 0
	v_add_f32_e32 v0, 1.0, v0
	v_rcp_f32_e32 v12, v0
	v_mul_f32_e32 v0, 0x3d372713, v9
	v_mul_f32_e32 v0, v9, v0
	v_fma_f32 v0, v9, v0, v9
	v_mul_f32_e32 v0, 0x3f4c422a, v0
	v_add_f32_e32 v0, v0, v0
	v_mul_f32_e32 v0, 0x3fb8aa3b, v0
	v_exp_f32_e32 v0, v0
	v_pk_mul_f32 v[8:9], v[8:9], 0.5 op_sel_hi:[1,0]
	v_add_f32_e32 v0, 1.0, v0
	v_rcp_f32_e32 v13, v0
	s_nop 0
	v_pk_fma_f32 v[12:13], v[12:13], 2.0, 1.0 op_sel_hi:[1,0,0] neg_lo:[1,0,0] neg_hi:[1,0,0]
	s_nop 0
	v_pk_add_f32 v[12:13], v[12:13], 1.0 op_sel_hi:[1,0]
	s_nop 0
	v_pk_mul_f32 v[8:9], v[8:9], v[12:13]
	v_mov_b64_e32 v[12:13], v[64:65]
	v_cvt_pk_bf16_f32 v6, v8, v9
	s_waitcnt lgkmcnt(0)
	v_mul_f32_e32 v0, 0x3d372713, v12
	v_mul_f32_e32 v0, v12, v0
	v_fma_f32 v0, v12, v0, v12
	v_mul_f32_e32 v0, 0x3f4c422a, v0
	v_add_f32_e32 v0, v0, v0
	v_mul_f32_e32 v0, 0x3fb8aa3b, v0
	v_exp_f32_e32 v0, v0
	s_nop 0
	v_add_f32_e32 v0, 1.0, v0
	v_rcp_f32_e32 v14, v0
	v_mul_f32_e32 v0, 0x3d372713, v13
	v_mul_f32_e32 v0, v13, v0
	v_fma_f32 v0, v13, v0, v13
	v_mul_f32_e32 v0, 0x3f4c422a, v0
	v_add_f32_e32 v0, v0, v0
	v_mul_f32_e32 v0, 0x3fb8aa3b, v0
	v_exp_f32_e32 v0, v0
	v_pk_mul_f32 v[12:13], v[12:13], 0.5 op_sel_hi:[1,0]
	v_add_f32_e32 v0, 1.0, v0
	v_rcp_f32_e32 v15, v0
	s_nop 0
	v_pk_fma_f32 v[14:15], v[14:15], 2.0, 1.0 op_sel_hi:[1,0,0] neg_lo:[1,0,0] neg_hi:[1,0,0]
	s_nop 0
	v_pk_add_f32 v[14:15], v[14:15], 1.0 op_sel_hi:[1,0]
	s_nop 0
	v_pk_mul_f32 v[12:13], v[12:13], v[14:15]
	s_nop 0
	v_cvt_pk_bf16_f32 v7, v12, v13
	global_store_dwordx4 v[2:3], v[4:7], off offset:48
	s_nop 1
	v_mov_b64_e32 v[4:5], v[98:99]
	s_waitcnt lgkmcnt(0)
	v_mul_f32_e32 v0, 0x3d372713, v4
	v_mul_f32_e32 v0, v4, v0
	v_fma_f32 v0, v4, v0, v4
	v_mul_f32_e32 v0, 0x3f4c422a, v0
	v_add_f32_e32 v0, v0, v0
	v_mul_f32_e32 v0, 0x3fb8aa3b, v0
	v_exp_f32_e32 v0, v0
	s_nop 0
	v_add_f32_e32 v0, 1.0, v0
	v_rcp_f32_e32 v6, v0
	v_mul_f32_e32 v0, 0x3d372713, v5
	v_mul_f32_e32 v0, v5, v0
	v_fma_f32 v0, v5, v0, v5
	v_mul_f32_e32 v0, 0x3f4c422a, v0
	v_add_f32_e32 v0, v0, v0
	v_mul_f32_e32 v0, 0x3fb8aa3b, v0
	v_exp_f32_e32 v0, v0
	v_pk_mul_f32 v[4:5], v[4:5], 0.5 op_sel_hi:[1,0]
	v_add_f32_e32 v0, 1.0, v0
	v_rcp_f32_e32 v7, v0
	s_nop 0
	v_pk_fma_f32 v[6:7], v[6:7], 2.0, 1.0 op_sel_hi:[1,0,0] neg_lo:[1,0,0] neg_hi:[1,0,0]
	s_nop 0
	v_pk_add_f32 v[6:7], v[6:7], 1.0 op_sel_hi:[1,0]
	s_nop 0
	v_pk_mul_f32 v[4:5], v[4:5], v[6:7]
	v_mov_b64_e32 v[6:7], v[100:101]
	v_cvt_pk_bf16_f32 v4, v4, v5
	s_waitcnt lgkmcnt(0)
	v_mul_f32_e32 v0, 0x3d372713, v6
	v_mul_f32_e32 v0, v6, v0
	v_fma_f32 v0, v6, v0, v6
	v_mul_f32_e32 v0, 0x3f4c422a, v0
	v_add_f32_e32 v0, v0, v0
	v_mul_f32_e32 v0, 0x3fb8aa3b, v0
	v_exp_f32_e32 v0, v0
	s_nop 0
	v_add_f32_e32 v0, 1.0, v0
	v_rcp_f32_e32 v8, v0
	v_mul_f32_e32 v0, 0x3d372713, v7
	v_mul_f32_e32 v0, v7, v0
	v_fma_f32 v0, v7, v0, v7
	v_mul_f32_e32 v0, 0x3f4c422a, v0
	v_add_f32_e32 v0, v0, v0
	v_mul_f32_e32 v0, 0x3fb8aa3b, v0
	v_exp_f32_e32 v0, v0
	v_pk_mul_f32 v[6:7], v[6:7], 0.5 op_sel_hi:[1,0]
	v_add_f32_e32 v0, 1.0, v0
	v_rcp_f32_e32 v9, v0
	s_nop 0
	v_pk_fma_f32 v[8:9], v[8:9], 2.0, 1.0 op_sel_hi:[1,0,0] neg_lo:[1,0,0] neg_hi:[1,0,0]
	s_nop 0
	v_pk_add_f32 v[8:9], v[8:9], 1.0 op_sel_hi:[1,0]
	s_nop 0
	v_pk_mul_f32 v[6:7], v[6:7], v[8:9]
	v_mov_b64_e32 v[8:9], v[102:103]
	v_cvt_pk_bf16_f32 v5, v6, v7
	s_waitcnt lgkmcnt(0)
	v_mul_f32_e32 v0, 0x3d372713, v8
	v_mul_f32_e32 v0, v8, v0
	v_fma_f32 v0, v8, v0, v8
	v_mul_f32_e32 v0, 0x3f4c422a, v0
	v_add_f32_e32 v0, v0, v0
	v_mul_f32_e32 v0, 0x3fb8aa3b, v0
	v_exp_f32_e32 v0, v0
	s_nop 0
	v_add_f32_e32 v0, 1.0, v0
	v_rcp_f32_e32 v12, v0
	v_mul_f32_e32 v0, 0x3d372713, v9
	v_mul_f32_e32 v0, v9, v0
	v_fma_f32 v0, v9, v0, v9
	v_mul_f32_e32 v0, 0x3f4c422a, v0
	v_add_f32_e32 v0, v0, v0
	v_mul_f32_e32 v0, 0x3fb8aa3b, v0
	v_exp_f32_e32 v0, v0
	v_pk_mul_f32 v[8:9], v[8:9], 0.5 op_sel_hi:[1,0]
	v_add_f32_e32 v0, 1.0, v0
	v_rcp_f32_e32 v13, v0
	s_nop 0
	v_pk_fma_f32 v[12:13], v[12:13], 2.0, 1.0 op_sel_hi:[1,0,0] neg_lo:[1,0,0] neg_hi:[1,0,0]
	s_nop 0
	v_pk_add_f32 v[12:13], v[12:13], 1.0 op_sel_hi:[1,0]
	s_nop 0
	v_pk_mul_f32 v[8:9], v[8:9], v[12:13]
	v_mov_b64_e32 v[12:13], v[104:105]
	v_cvt_pk_bf16_f32 v6, v8, v9
	s_waitcnt lgkmcnt(0)
	v_mul_f32_e32 v0, 0x3d372713, v12
	v_mul_f32_e32 v0, v12, v0
	v_fma_f32 v0, v12, v0, v12
	v_mul_f32_e32 v0, 0x3f4c422a, v0
	v_add_f32_e32 v0, v0, v0
	v_mul_f32_e32 v0, 0x3fb8aa3b, v0
	v_exp_f32_e32 v0, v0
	s_nop 0
	v_add_f32_e32 v0, 1.0, v0
	v_rcp_f32_e32 v14, v0
	v_mul_f32_e32 v0, 0x3d372713, v13
	v_mul_f32_e32 v0, v13, v0
	v_fma_f32 v0, v13, v0, v13
	v_mul_f32_e32 v0, 0x3f4c422a, v0
	v_add_f32_e32 v0, v0, v0
	v_mul_f32_e32 v0, 0x3fb8aa3b, v0
	v_exp_f32_e32 v0, v0
	v_pk_mul_f32 v[12:13], v[12:13], 0.5 op_sel_hi:[1,0]
	v_add_f32_e32 v0, 1.0, v0
	v_rcp_f32_e32 v15, v0
	s_nop 0
	v_pk_fma_f32 v[14:15], v[14:15], 2.0, 1.0 op_sel_hi:[1,0,0] neg_lo:[1,0,0] neg_hi:[1,0,0]
	s_nop 0
	v_pk_add_f32 v[14:15], v[14:15], 1.0 op_sel_hi:[1,0]
	s_nop 0
	v_pk_mul_f32 v[12:13], v[12:13], v[14:15]
	s_nop 0
	v_cvt_pk_bf16_f32 v7, v12, v13
	global_store_dwordx4 v[2:3], v[4:7], off offset:64
	s_nop 1
	v_mov_b64_e32 v[4:5], v[106:107]
	s_waitcnt lgkmcnt(0)
	v_mul_f32_e32 v0, 0x3d372713, v4
	v_mul_f32_e32 v0, v4, v0
	v_fma_f32 v0, v4, v0, v4
	v_mul_f32_e32 v0, 0x3f4c422a, v0
	v_add_f32_e32 v0, v0, v0
	v_mul_f32_e32 v0, 0x3fb8aa3b, v0
	v_exp_f32_e32 v0, v0
	s_nop 0
	v_add_f32_e32 v0, 1.0, v0
	v_rcp_f32_e32 v6, v0
	v_mul_f32_e32 v0, 0x3d372713, v5
	v_mul_f32_e32 v0, v5, v0
	v_fma_f32 v0, v5, v0, v5
	v_mul_f32_e32 v0, 0x3f4c422a, v0
	v_add_f32_e32 v0, v0, v0
	v_mul_f32_e32 v0, 0x3fb8aa3b, v0
	v_exp_f32_e32 v0, v0
	v_pk_mul_f32 v[4:5], v[4:5], 0.5 op_sel_hi:[1,0]
	v_add_f32_e32 v0, 1.0, v0
	v_rcp_f32_e32 v7, v0
	s_nop 0
	v_pk_fma_f32 v[6:7], v[6:7], 2.0, 1.0 op_sel_hi:[1,0,0] neg_lo:[1,0,0] neg_hi:[1,0,0]
	s_nop 0
	v_pk_add_f32 v[6:7], v[6:7], 1.0 op_sel_hi:[1,0]
	s_nop 0
	v_pk_mul_f32 v[4:5], v[4:5], v[6:7]
	v_mov_b64_e32 v[6:7], v[108:109]
	v_cvt_pk_bf16_f32 v4, v4, v5
	s_waitcnt lgkmcnt(0)
	v_mul_f32_e32 v0, 0x3d372713, v6
	v_mul_f32_e32 v0, v6, v0
	v_fma_f32 v0, v6, v0, v6
	v_mul_f32_e32 v0, 0x3f4c422a, v0
	v_add_f32_e32 v0, v0, v0
	v_mul_f32_e32 v0, 0x3fb8aa3b, v0
	v_exp_f32_e32 v0, v0
	s_nop 0
	v_add_f32_e32 v0, 1.0, v0
	v_rcp_f32_e32 v8, v0
	v_mul_f32_e32 v0, 0x3d372713, v7
	v_mul_f32_e32 v0, v7, v0
	v_fma_f32 v0, v7, v0, v7
	v_mul_f32_e32 v0, 0x3f4c422a, v0
	v_add_f32_e32 v0, v0, v0
	v_mul_f32_e32 v0, 0x3fb8aa3b, v0
	v_exp_f32_e32 v0, v0
	v_pk_mul_f32 v[6:7], v[6:7], 0.5 op_sel_hi:[1,0]
	v_add_f32_e32 v0, 1.0, v0
	v_rcp_f32_e32 v9, v0
	s_nop 0
	v_pk_fma_f32 v[8:9], v[8:9], 2.0, 1.0 op_sel_hi:[1,0,0] neg_lo:[1,0,0] neg_hi:[1,0,0]
	s_nop 0
	v_pk_add_f32 v[8:9], v[8:9], 1.0 op_sel_hi:[1,0]
	s_nop 0
	v_pk_mul_f32 v[6:7], v[6:7], v[8:9]
	v_mov_b64_e32 v[8:9], v[110:111]
	v_cvt_pk_bf16_f32 v5, v6, v7
	s_waitcnt lgkmcnt(0)
	v_mul_f32_e32 v0, 0x3d372713, v8
	v_mul_f32_e32 v0, v8, v0
	v_fma_f32 v0, v8, v0, v8
	v_mul_f32_e32 v0, 0x3f4c422a, v0
	v_add_f32_e32 v0, v0, v0
	v_mul_f32_e32 v0, 0x3fb8aa3b, v0
	v_exp_f32_e32 v0, v0
	s_nop 0
	v_add_f32_e32 v0, 1.0, v0
	v_rcp_f32_e32 v12, v0
	v_mul_f32_e32 v0, 0x3d372713, v9
	v_mul_f32_e32 v0, v9, v0
	v_fma_f32 v0, v9, v0, v9
	v_mul_f32_e32 v0, 0x3f4c422a, v0
	v_add_f32_e32 v0, v0, v0
	v_mul_f32_e32 v0, 0x3fb8aa3b, v0
	v_exp_f32_e32 v0, v0
	v_pk_mul_f32 v[8:9], v[8:9], 0.5 op_sel_hi:[1,0]
	v_add_f32_e32 v0, 1.0, v0
	v_rcp_f32_e32 v13, v0
	s_nop 0
	v_pk_fma_f32 v[12:13], v[12:13], 2.0, 1.0 op_sel_hi:[1,0,0] neg_lo:[1,0,0] neg_hi:[1,0,0]
	s_nop 0
	v_pk_add_f32 v[12:13], v[12:13], 1.0 op_sel_hi:[1,0]
	s_nop 0
	v_pk_mul_f32 v[8:9], v[8:9], v[12:13]
	v_mov_b64_e32 v[12:13], v[112:113]
	v_cvt_pk_bf16_f32 v6, v8, v9
	s_waitcnt lgkmcnt(0)
	v_mul_f32_e32 v0, 0x3d372713, v12
	v_mul_f32_e32 v0, v12, v0
	v_fma_f32 v0, v12, v0, v12
	v_mul_f32_e32 v0, 0x3f4c422a, v0
	v_add_f32_e32 v0, v0, v0
	v_mul_f32_e32 v0, 0x3fb8aa3b, v0
	v_exp_f32_e32 v0, v0
	s_nop 0
	v_add_f32_e32 v0, 1.0, v0
	v_rcp_f32_e32 v14, v0
	v_mul_f32_e32 v0, 0x3d372713, v13
	v_mul_f32_e32 v0, v13, v0
	v_fma_f32 v0, v13, v0, v13
	v_mul_f32_e32 v0, 0x3f4c422a, v0
	v_add_f32_e32 v0, v0, v0
	v_mul_f32_e32 v0, 0x3fb8aa3b, v0
	v_exp_f32_e32 v0, v0
	v_pk_mul_f32 v[12:13], v[12:13], 0.5 op_sel_hi:[1,0]
	v_add_f32_e32 v0, 1.0, v0
	v_rcp_f32_e32 v15, v0
	s_nop 0
	v_pk_fma_f32 v[14:15], v[14:15], 2.0, 1.0 op_sel_hi:[1,0,0] neg_lo:[1,0,0] neg_hi:[1,0,0]
	s_nop 0
	v_pk_add_f32 v[14:15], v[14:15], 1.0 op_sel_hi:[1,0]
	s_nop 0
	v_pk_mul_f32 v[12:13], v[12:13], v[14:15]
	s_nop 0
	v_cvt_pk_bf16_f32 v7, v12, v13
	global_store_dwordx4 v[2:3], v[4:7], off offset:80
	s_nop 1
	v_mov_b64_e32 v[4:5], v[114:115]
	s_waitcnt lgkmcnt(0)
	v_mul_f32_e32 v0, 0x3d372713, v4
	v_mul_f32_e32 v0, v4, v0
	v_fma_f32 v0, v4, v0, v4
	v_mul_f32_e32 v0, 0x3f4c422a, v0
	v_add_f32_e32 v0, v0, v0
	v_mul_f32_e32 v0, 0x3fb8aa3b, v0
	v_exp_f32_e32 v0, v0
	s_nop 0
	v_add_f32_e32 v0, 1.0, v0
	v_rcp_f32_e32 v6, v0
	v_mul_f32_e32 v0, 0x3d372713, v5
	v_mul_f32_e32 v0, v5, v0
	v_fma_f32 v0, v5, v0, v5
	v_mul_f32_e32 v0, 0x3f4c422a, v0
	v_add_f32_e32 v0, v0, v0
	v_mul_f32_e32 v0, 0x3fb8aa3b, v0
	v_exp_f32_e32 v0, v0
	v_pk_mul_f32 v[4:5], v[4:5], 0.5 op_sel_hi:[1,0]
	v_add_f32_e32 v0, 1.0, v0
	v_rcp_f32_e32 v7, v0
	s_nop 0
	v_pk_fma_f32 v[6:7], v[6:7], 2.0, 1.0 op_sel_hi:[1,0,0] neg_lo:[1,0,0] neg_hi:[1,0,0]
	s_nop 0
	v_pk_add_f32 v[6:7], v[6:7], 1.0 op_sel_hi:[1,0]
	s_nop 0
	v_pk_mul_f32 v[4:5], v[4:5], v[6:7]
	v_mov_b64_e32 v[6:7], v[116:117]
	v_cvt_pk_bf16_f32 v4, v4, v5
	s_waitcnt lgkmcnt(0)
	v_mul_f32_e32 v0, 0x3d372713, v6
	v_mul_f32_e32 v0, v6, v0
	v_fma_f32 v0, v6, v0, v6
	v_mul_f32_e32 v0, 0x3f4c422a, v0
	v_add_f32_e32 v0, v0, v0
	v_mul_f32_e32 v0, 0x3fb8aa3b, v0
	v_exp_f32_e32 v0, v0
	s_nop 0
	v_add_f32_e32 v0, 1.0, v0
	v_rcp_f32_e32 v8, v0
	v_mul_f32_e32 v0, 0x3d372713, v7
	v_mul_f32_e32 v0, v7, v0
	v_fma_f32 v0, v7, v0, v7
	v_mul_f32_e32 v0, 0x3f4c422a, v0
	v_add_f32_e32 v0, v0, v0
	v_mul_f32_e32 v0, 0x3fb8aa3b, v0
	v_exp_f32_e32 v0, v0
	v_pk_mul_f32 v[6:7], v[6:7], 0.5 op_sel_hi:[1,0]
	v_add_f32_e32 v0, 1.0, v0
	v_rcp_f32_e32 v9, v0
	s_nop 0
	v_pk_fma_f32 v[8:9], v[8:9], 2.0, 1.0 op_sel_hi:[1,0,0] neg_lo:[1,0,0] neg_hi:[1,0,0]
	s_nop 0
	v_pk_add_f32 v[8:9], v[8:9], 1.0 op_sel_hi:[1,0]
	s_nop 0
	v_pk_mul_f32 v[6:7], v[6:7], v[8:9]
	v_mov_b64_e32 v[8:9], v[118:119]
	v_cvt_pk_bf16_f32 v5, v6, v7
	s_waitcnt lgkmcnt(0)
	v_mul_f32_e32 v0, 0x3d372713, v8
	v_mul_f32_e32 v0, v8, v0
	v_fma_f32 v0, v8, v0, v8
	v_mul_f32_e32 v0, 0x3f4c422a, v0
	v_add_f32_e32 v0, v0, v0
	v_mul_f32_e32 v0, 0x3fb8aa3b, v0
	v_exp_f32_e32 v0, v0
	s_nop 0
	v_add_f32_e32 v0, 1.0, v0
	v_rcp_f32_e32 v12, v0
	v_mul_f32_e32 v0, 0x3d372713, v9
	v_mul_f32_e32 v0, v9, v0
	v_fma_f32 v0, v9, v0, v9
	v_mul_f32_e32 v0, 0x3f4c422a, v0
	v_add_f32_e32 v0, v0, v0
	v_mul_f32_e32 v0, 0x3fb8aa3b, v0
	v_exp_f32_e32 v0, v0
	v_pk_mul_f32 v[8:9], v[8:9], 0.5 op_sel_hi:[1,0]
	v_add_f32_e32 v0, 1.0, v0
	v_rcp_f32_e32 v13, v0
	s_nop 0
	v_pk_fma_f32 v[12:13], v[12:13], 2.0, 1.0 op_sel_hi:[1,0,0] neg_lo:[1,0,0] neg_hi:[1,0,0]
	s_nop 0
	v_pk_add_f32 v[12:13], v[12:13], 1.0 op_sel_hi:[1,0]
	s_nop 0
	v_pk_mul_f32 v[8:9], v[8:9], v[12:13]
	v_mov_b64_e32 v[12:13], v[120:121]
	v_cvt_pk_bf16_f32 v6, v8, v9
	s_waitcnt lgkmcnt(0)
	v_mul_f32_e32 v0, 0x3d372713, v12
	v_mul_f32_e32 v0, v12, v0
	v_fma_f32 v0, v12, v0, v12
	v_mul_f32_e32 v0, 0x3f4c422a, v0
	v_add_f32_e32 v0, v0, v0
	v_mul_f32_e32 v0, 0x3fb8aa3b, v0
	v_exp_f32_e32 v0, v0
	s_nop 0
	v_add_f32_e32 v0, 1.0, v0
	v_rcp_f32_e32 v14, v0
	v_mul_f32_e32 v0, 0x3d372713, v13
	v_mul_f32_e32 v0, v13, v0
	v_fma_f32 v0, v13, v0, v13
	v_mul_f32_e32 v0, 0x3f4c422a, v0
	v_add_f32_e32 v0, v0, v0
	v_mul_f32_e32 v0, 0x3fb8aa3b, v0
	v_exp_f32_e32 v0, v0
	v_pk_mul_f32 v[12:13], v[12:13], 0.5 op_sel_hi:[1,0]
	v_add_f32_e32 v0, 1.0, v0
	v_rcp_f32_e32 v15, v0
	s_nop 0
	v_pk_fma_f32 v[14:15], v[14:15], 2.0, 1.0 op_sel_hi:[1,0,0] neg_lo:[1,0,0] neg_hi:[1,0,0]
	s_nop 0
	v_pk_add_f32 v[14:15], v[14:15], 1.0 op_sel_hi:[1,0]
	s_nop 0
	v_pk_mul_f32 v[12:13], v[12:13], v[14:15]
	s_nop 0
	v_cvt_pk_bf16_f32 v7, v12, v13
	global_store_dwordx4 v[2:3], v[4:7], off offset:96
	s_nop 1
	v_mov_b64_e32 v[4:5], v[122:123]
	s_waitcnt lgkmcnt(0)
	v_mul_f32_e32 v0, 0x3d372713, v4
	v_mul_f32_e32 v0, v4, v0
	v_fma_f32 v0, v4, v0, v4
	v_mul_f32_e32 v0, 0x3f4c422a, v0
	v_add_f32_e32 v0, v0, v0
	v_mul_f32_e32 v0, 0x3fb8aa3b, v0
	v_exp_f32_e32 v0, v0
	s_nop 0
	v_add_f32_e32 v0, 1.0, v0
	v_rcp_f32_e32 v6, v0
	v_mul_f32_e32 v0, 0x3d372713, v5
	v_mul_f32_e32 v0, v5, v0
	v_fma_f32 v0, v5, v0, v5
	v_mul_f32_e32 v0, 0x3f4c422a, v0
	v_add_f32_e32 v0, v0, v0
	v_mul_f32_e32 v0, 0x3fb8aa3b, v0
	v_exp_f32_e32 v0, v0
	v_pk_mul_f32 v[4:5], v[4:5], 0.5 op_sel_hi:[1,0]
	v_add_f32_e32 v0, 1.0, v0
	v_rcp_f32_e32 v7, v0
	s_nop 0
	v_pk_fma_f32 v[6:7], v[6:7], 2.0, 1.0 op_sel_hi:[1,0,0] neg_lo:[1,0,0] neg_hi:[1,0,0]
	s_nop 0
	v_pk_add_f32 v[6:7], v[6:7], 1.0 op_sel_hi:[1,0]
	s_nop 0
	v_pk_mul_f32 v[4:5], v[4:5], v[6:7]
	v_mov_b64_e32 v[6:7], v[124:125]
	v_cvt_pk_bf16_f32 v4, v4, v5
	s_waitcnt lgkmcnt(0)
	v_mul_f32_e32 v0, 0x3d372713, v6
	v_mul_f32_e32 v0, v6, v0
	v_fma_f32 v0, v6, v0, v6
	v_mul_f32_e32 v0, 0x3f4c422a, v0
	v_add_f32_e32 v0, v0, v0
	v_mul_f32_e32 v0, 0x3fb8aa3b, v0
	v_exp_f32_e32 v0, v0
	s_nop 0
	v_add_f32_e32 v0, 1.0, v0
	v_rcp_f32_e32 v8, v0
	v_mul_f32_e32 v0, 0x3d372713, v7
	v_mul_f32_e32 v0, v7, v0
	v_fma_f32 v0, v7, v0, v7
	v_mul_f32_e32 v0, 0x3f4c422a, v0
	v_add_f32_e32 v0, v0, v0
	v_mul_f32_e32 v0, 0x3fb8aa3b, v0
	v_exp_f32_e32 v0, v0
	v_pk_mul_f32 v[6:7], v[6:7], 0.5 op_sel_hi:[1,0]
	v_add_f32_e32 v0, 1.0, v0
	v_rcp_f32_e32 v9, v0
	s_nop 0
	v_pk_fma_f32 v[8:9], v[8:9], 2.0, 1.0 op_sel_hi:[1,0,0] neg_lo:[1,0,0] neg_hi:[1,0,0]
	s_nop 0
	v_pk_add_f32 v[8:9], v[8:9], 1.0 op_sel_hi:[1,0]
	s_nop 0
	v_pk_mul_f32 v[6:7], v[6:7], v[8:9]
	v_mov_b64_e32 v[8:9], v[126:127]
	v_cvt_pk_bf16_f32 v5, v6, v7
	s_waitcnt lgkmcnt(0)
	v_mul_f32_e32 v0, 0x3d372713, v8
	v_mul_f32_e32 v0, v8, v0
	v_fma_f32 v0, v8, v0, v8
	v_mul_f32_e32 v0, 0x3f4c422a, v0
	v_add_f32_e32 v0, v0, v0
	v_mul_f32_e32 v0, 0x3fb8aa3b, v0
	v_exp_f32_e32 v0, v0
	s_nop 0
	v_add_f32_e32 v0, 1.0, v0
	v_rcp_f32_e32 v12, v0
	v_mul_f32_e32 v0, 0x3d372713, v9
	v_mul_f32_e32 v0, v9, v0
	v_fma_f32 v0, v9, v0, v9
	v_mul_f32_e32 v0, 0x3f4c422a, v0
	v_add_f32_e32 v0, v0, v0
	v_mul_f32_e32 v0, 0x3fb8aa3b, v0
	v_exp_f32_e32 v0, v0
	v_pk_mul_f32 v[8:9], v[8:9], 0.5 op_sel_hi:[1,0]
	v_add_f32_e32 v0, 1.0, v0
	v_rcp_f32_e32 v13, v0
	s_nop 0
	v_pk_fma_f32 v[12:13], v[12:13], 2.0, 1.0 op_sel_hi:[1,0,0] neg_lo:[1,0,0] neg_hi:[1,0,0]
	s_nop 0
	v_pk_add_f32 v[12:13], v[12:13], 1.0 op_sel_hi:[1,0]
	s_nop 0
	v_pk_mul_f32 v[8:9], v[8:9], v[12:13]
	v_mov_b64_e32 v[12:13], v[128:129]
	v_cvt_pk_bf16_f32 v6, v8, v9
	s_waitcnt lgkmcnt(0)
	v_mul_f32_e32 v0, 0x3d372713, v12
	v_mul_f32_e32 v0, v12, v0
	v_fma_f32 v0, v12, v0, v12
	v_mul_f32_e32 v0, 0x3f4c422a, v0
	v_add_f32_e32 v0, v0, v0
	v_mul_f32_e32 v0, 0x3fb8aa3b, v0
	v_exp_f32_e32 v0, v0
	s_nop 0
	v_add_f32_e32 v0, 1.0, v0
	v_rcp_f32_e32 v14, v0
	v_mul_f32_e32 v0, 0x3d372713, v13
	v_mul_f32_e32 v0, v13, v0
	v_fma_f32 v0, v13, v0, v13
	v_mul_f32_e32 v0, 0x3f4c422a, v0
	v_add_f32_e32 v0, v0, v0
	v_mul_f32_e32 v0, 0x3fb8aa3b, v0
	v_exp_f32_e32 v0, v0
	v_pk_mul_f32 v[12:13], v[12:13], 0.5 op_sel_hi:[1,0]
	v_add_f32_e32 v0, 1.0, v0
	v_rcp_f32_e32 v15, v0
	s_nop 0
	v_pk_fma_f32 v[14:15], v[14:15], 2.0, 1.0 op_sel_hi:[1,0,0] neg_lo:[1,0,0] neg_hi:[1,0,0]
	s_nop 0
	v_pk_add_f32 v[14:15], v[14:15], 1.0 op_sel_hi:[1,0]
	s_nop 0
	v_pk_mul_f32 v[12:13], v[12:13], v[14:15]
	s_nop 0
	v_cvt_pk_bf16_f32 v7, v12, v13
	global_store_dwordx4 v[2:3], v[4:7], off offset:112

.LBB0_470:
	s_andn2_b64 vcc, exec, s[12:13]
	s_cbranch_vccnz .LBB0_488
	s_cmp_eq_u32 s19, 5
	s_cselect_b64 s[14:15], -1, 0
	v_readlane_b32 s72, v250, 18
	s_and_b64 s[10:11], s[14:15], exec
	v_readlane_b32 s76, v250, 22
	v_readlane_b32 s78, v250, 24
	v_readlane_b32 s77, v250, 23
	v_readlane_b32 s79, v250, 25
	s_cselect_b32 s11, s76, s78
	v_ashrrev_i32_e32 v27, 31, v26
	s_cselect_b32 s10, s77, s79
	s_add_u32 s12, s11, s2
	v_lshl_add_u64 v[2:3], v[26:27], 4, s[0:1]
	s_addc_u32 s13, s10, s3
	v_or_b32_e32 v2, v2, v25
	v_readlane_b32 s10, v251, 55
	v_lshlrev_b64 v[2:3], 16, v[2:3]
	v_readlane_b32 s11, v251, 56
	v_lshlrev_b32_e32 v4, 8, v0
	v_mov_b32_e32 v5, v1
	v_lshl_add_u64 v[2:3], s[10:11], 0, v[2:3]
	v_lshl_add_u64 v[34:35], v[2:3], 0, v[4:5]
	ds_read2_b32 v[14:15], v155 offset0:6 offset1:7
	ds_read2_b32 v[16:17], v155 offset0:14 offset1:15
	ds_read2_b32 v[22:23], v155 offset0:22 offset1:23
	ds_read2_b32 v[50:51], v155 offset0:16 offset1:17
	ds_read2_b32 v[48:49], v155 offset0:18 offset1:19
	s_waitcnt vmcnt(5)
	ds_read2_b32 v[108:109], v155 offset1:1
	ds_read2_b32 v[18:19], v155 offset0:8 offset1:9
	ds_read2_b32 v[38:39], v155 offset0:24 offset1:25
	ds_read2_b32 v[40:41], v155 offset0:26 offset1:27
	ds_read2_b32 v[42:43], v155 offset0:28 offset1:29
	ds_read2_b32 v[46:47], v155 offset0:20 offset1:21
	ds_read2_b32 v[44:45], v155 offset0:30 offset1:31
	global_load_dwordx4 v[2:5], v1, s[12:13] offset:16
	global_load_dwordx4 v[6:9], v1, s[12:13] offset:48
	global_load_dwordx4 v[10:13], v1, s[12:13] offset:32
	global_load_dwordx4 v[104:107], v1, s[12:13]
	global_load_dwordx4 v[124:127], v1, s[12:13]
	global_load_dwordx4 v[142:145], v1, s[12:13] offset:16
	global_load_dwordx4 v[158:161], v1, s[12:13] offset:32
	global_load_dwordx4 v[162:165], v1, s[12:13] offset:48
	global_load_dwordx4 v[166:169], v1, s[12:13] offset:64
	global_load_dwordx4 v[170:173], v1, s[12:13] offset:80
	global_load_dwordx4 v[174:177], v1, s[12:13] offset:96
	global_load_dwordx4 v[178:181], v1, s[12:13] offset:112
	v_lshrrev_b32_e32 v248, 6, v0
	v_lshlrev_b32_e32 v248, 6, v248
	s_and_saveexec_b64 s[16:17], s[42:43]
	global_load_dwordx4 v[182:185], v248, s[62:63]
	global_load_dwordx4 v[186:189], v248, s[62:63] offset:16
	global_load_dwordx4 v[190:193], v248, s[62:63] offset:32
	global_load_dwordx4 v[194:197], v248, s[62:63] offset:48
	global_load_dwordx4 v[208:211], v[136:137], off
	global_load_dwordx4 v[214:217], v[136:137], off offset:16
	global_load_dwordx4 v[228:231], v[136:137], off offset:32
	global_load_dwordx4 v[244:247], v[136:137], off offset:48
	s_or_b64 exec, exec, s[16:17]
	s_waitcnt lgkmcnt(6)
	v_pk_mul_f32 v[98:99], v[108:109], v[108:109]
	s_waitcnt lgkmcnt(5)
	v_pk_mul_f32 v[64:65], v[18:19], v[18:19]
	v_mov_b32_e32 v100, v108
	v_mov_b32_e32 v101, v19
	v_mov_b32_e32 v19, v109
	ds_read2_b32 v[108:109], v155 offset0:2 offset1:3
	s_waitcnt vmcnt(22)
	ds_read2_b32 v[118:119], v155 offset0:12 offset1:13
	v_add_f32_e32 v27, v98, v99
	v_pk_mul_f32 v[58:59], v[50:51], v[50:51]
	v_pk_mul_f32 v[60:61], v[48:49], v[48:49]
	s_waitcnt lgkmcnt(3)
	v_pk_mul_f32 v[62:63], v[46:47], v[46:47]
	v_pk_mul_f32 v[54:55], v[22:23], v[22:23]
	v_pk_mul_f32 v[56:57], v[38:39], v[38:39]
	v_pk_mul_f32 v[20:21], v[40:41], v[40:41]
	v_pk_mul_f32 v[36:37], v[42:43], v[42:43]
	s_waitcnt lgkmcnt(2)
	v_pk_mul_f32 v[52:53], v[44:45], v[44:45]
	s_cmp_eq_u32 s19, 6
	s_cselect_b64 s[10:11], -1, 0
	s_and_b64 s[10:11], s[10:11], s[40:41]
	v_readlane_b32 s73, v250, 19
	v_readlane_b32 s74, v250, 20
	v_readlane_b32 s75, v250, 21
	v_readlane_b32 s80, v250, 26
	v_readlane_b32 s81, v250, 27
	v_readlane_b32 s82, v250, 28
	v_readlane_b32 s83, v250, 29
	v_readlane_b32 s84, v250, 30
	v_readlane_b32 s85, v250, 31
	v_readlane_b32 s86, v250, 32
	v_readlane_b32 s87, v250, 33
	s_waitcnt lgkmcnt(0)
	v_pk_mul_f32 v[120:121], v[118:119], v[118:119]
	s_waitcnt vmcnt(17)
	v_mov_b32_e32 v103, v11
	s_waitcnt vmcnt(0)
	v_mov_b32_e32 v102, v104
	v_mov_b32_e32 v11, v105
	ds_read2_b32 v[104:105], v155 offset0:10 offset1:11
	v_mov_b32_e32 v116, v106
	v_mov_b32_e32 v117, v13
	v_mov_b32_e32 v13, v107
	ds_read2_b32 v[106:107], v155 offset0:4 offset1:5
	v_pk_mul_f32 v[110:111], v[108:109], v[108:109]
	s_waitcnt lgkmcnt(1)
	v_pk_mul_f32 v[112:113], v[104:105], v[104:105]
	v_add_f32_e32 v27, v27, v110
	v_mov_b32_e32 v114, v108
	v_mov_b32_e32 v115, v105
	v_mov_b32_e32 v105, v109
	s_waitcnt lgkmcnt(0)
	v_pk_mul_f32 v[108:109], v[106:107], v[106:107]
	v_add_f32_e32 v27, v27, v111
	v_add_f32_e32 v27, v27, v108
	v_add_f32_e32 v27, v27, v109
	v_fmac_f32_e32 v27, v14, v14
	v_fmac_f32_e32 v27, v15, v15
	v_add_f32_e32 v27, v27, v64
	v_add_f32_e32 v27, v27, v65
	v_add_f32_e32 v27, v27, v112
	v_add_f32_e32 v27, v27, v113
	v_add_f32_e32 v27, v27, v120
	v_add_f32_e32 v27, v27, v121
	v_fmac_f32_e32 v27, v16, v16
	v_fmac_f32_e32 v27, v17, v17
	v_add_f32_e32 v27, v27, v58
	v_add_f32_e32 v27, v27, v59
	v_add_f32_e32 v27, v27, v60
	v_add_f32_e32 v27, v27, v61
	v_add_f32_e32 v27, v27, v62
	v_add_f32_e32 v27, v27, v63
	v_add_f32_e32 v27, v27, v54
	v_add_f32_e32 v27, v27, v55
	v_add_f32_e32 v27, v27, v56
	v_add_f32_e32 v27, v27, v57
	v_add_f32_e32 v20, v27, v20
	v_add_f32_e32 v20, v20, v21
	v_add_f32_e32 v20, v20, v36
	v_add_f32_e32 v20, v20, v37
	v_add_f32_e32 v20, v20, v52
	v_add_f32_e32 v20, v20, v53
	v_fmamk_f32 v20, v20, 0x3d000000, v213
	v_cmp_gt_f32_e32 vcc, s54, v20
	v_mul_f32_e32 v21, 0x4b800000, v20
	s_nop 0
	v_cndmask_b32_e32 v20, v20, v21, vcc
	v_rsq_f32_e32 v20, v20
	s_nop 0
	v_mul_f32_e32 v21, 0x45800000, v20
	v_cndmask_b32_e32 v52, v20, v21, vcc
	v_pk_mul_f32 v[18:19], v[18:19], v[52:53] op_sel_hi:[1,0]
	v_pk_mul_f32 v[20:21], v[100:101], v[52:53] op_sel_hi:[1,0]
	v_pk_mul_f32 v[54:55], v[10:11], v[18:19]
	v_pk_mul_f32 v[10:11], v[114:115], v[52:53] op_sel_hi:[1,0]
	v_pk_mul_f32 v[60:61], v[102:103], v[20:21]
	v_pk_mul_f32 v[62:63], v[116:117], v[10:11]
	v_pk_mul_f32 v[10:11], v[104:105], v[52:53] op_sel_hi:[1,0]
	s_nop 0
	v_pk_mul_f32 v[56:57], v[12:13], v[10:11]
	v_mov_b32_e32 v10, v106
	v_mov_b32_e32 v11, v119
	v_pk_mul_f32 v[10:11], v[10:11], v[52:53] op_sel_hi:[1,0]
	v_mov_b32_e32 v12, v2
	v_mov_b32_e32 v13, v7
	v_mov_b32_e32 v119, v107
	v_mul_f32_e32 v2, v14, v52
	v_pk_mul_f32 v[64:65], v[12:13], v[10:11]
	v_pk_mul_f32 v[10:11], v[118:119], v[52:53] op_sel_hi:[1,0]
	v_mov_b32_e32 v7, v3
	v_mul_f32_e32 v20, v2, v4
	v_mul_f32_e32 v2, v16, v52
	v_mov_b32_e32 v14, v17
	v_pk_mul_f32 v[58:59], v[10:11], v[6:7]
	v_mul_f32_e32 v7, v2, v8
	v_pk_mul_f32 v[2:3], v[14:15], v[52:53] op_sel_hi:[1,0]
	v_mov_b32_e32 v4, v9
	v_pk_mul_f32 v[98:99], v[2:3], v[4:5]
	s_and_saveexec_b64 s[16:17], s[10:11]
	s_cbranch_execz .LBB0_473
	v_mov_b32_e32 v2, v60
	v_mov_b32_e32 v3, v55
	v_mov_b32_e32 v4, v62
	v_mov_b32_e32 v5, v57
	global_store_dwordx4 v[34:35], v[2:5], off
	v_mov_b32_e32 v18, v64
	v_mov_b32_e32 v19, v59
	v_mov_b32_e32 v2, v99
	v_mov_b32_e32 v3, v54
	v_mov_b32_e32 v4, v61
	v_mov_b32_e32 v5, v56
	global_store_dwordx4 v[34:35], v[2:5], off offset:28
	v_mov_b32_e32 v6, v65
	global_store_dwordx3 v[34:35], v[18:20], off offset:16
	v_mov_b32_e32 v4, v63
	v_mov_b32_e32 v5, v58
	global_store_dwordx4 v[34:35], v[4:7], off offset:44
	global_store_dword v[34:35], v98, off offset:60
.LBB0_473:
	s_or_b64 exec, exec, s[16:17]
	v_lshrrev_b32_e32 v2, 6, v0
	v_lshlrev_b32_e32 v27, 6, v2
	s_and_saveexec_b64 s[16:17], s[42:43]
	s_cbranch_execz .LBB0_475
	v_mov_b64_e32 v[16:17], v[194:195]
	v_mov_b64_e32 v[18:19], v[196:197]
	v_mov_b64_e32 v[2:3], v[190:191]
	v_mov_b64_e32 v[4:5], v[192:193]
	v_mov_b64_e32 v[8:9], v[186:187]
	v_mov_b64_e32 v[10:11], v[188:189]
	v_mov_b64_e32 v[12:13], v[182:183]
	v_mov_b64_e32 v[14:15], v[184:185]
	v_mov_b32_e32 v106, v54
	v_mov_b32_e32 v107, v61
	v_mul_f32_e32 v6, v7, v17
	v_mov_b32_e32 v112, v3
	v_mov_b32_e32 v110, v9
	v_mov_b32_e32 v108, v13
	v_mov_b32_e32 v109, v15
	v_pk_mul_f32 v[106:107], v[106:107], v[108:109]
	v_mov_b32_e32 v108, v56
	v_mov_b32_e32 v109, v63
	v_mov_b32_e32 v111, v11
	v_pk_mul_f32 v[108:109], v[108:109], v[110:111]
	v_mov_b32_e32 v110, v58
	v_mov_b32_e32 v111, v65
	v_mov_b32_e32 v113, v5
	v_mov_b32_e32 v36, v13
	v_mov_b32_e32 v37, v14
	v_mov_b32_e32 v100, v9
	v_mov_b32_e32 v101, v10
	v_mov_b32_e32 v104, v12
	v_mov_b32_e32 v105, v15
	v_mov_b32_e32 v13, v14
	v_mov_b32_e32 v14, v8
	v_mov_b32_e32 v15, v11
	v_mov_b32_e32 v9, v10
	v_mov_b32_e32 v10, v2
	v_mov_b32_e32 v11, v5
	v_pk_mul_f32 v[110:111], v[110:111], v[112:113]
	v_pk_mul_f32 v[112:113], v[98:99], v[18:19] op_sel:[1,0] op_sel_hi:[0,1]
	v_pk_mul_f32 v[18:19], v[98:99], v[18:19]
	v_mov_b32_e32 v102, v3
	v_mov_b32_e32 v103, v4
	v_pk_mul_f32 v[104:105], v[54:55], v[104:105]
	v_mov_b32_e32 v54, v60
	v_pk_mul_f32 v[14:15], v[56:57], v[14:15]
	v_mov_b32_e32 v56, v62
	v_pk_mul_f32 v[10:11], v[58:59], v[10:11]
	v_mov_b32_e32 v58, v64
	v_mov_b32_e32 v3, v4
	v_mul_f32_e32 v4, v20, v16
	v_mul_f32_e32 v20, v20, v17
	v_mul_f32_e32 v16, v7, v16
	v_mov_b32_e32 v5, v112
	v_mov_b32_e32 v7, v113
	v_mov_b32_e32 v17, v18
	v_mov_b32_e32 v21, v19
	v_pk_fma_f32 v[12:13], v[54:55], v[12:13], v[106:107] neg_lo:[0,0,1] neg_hi:[0,0,1]
	v_pk_fma_f32 v[8:9], v[56:57], v[8:9], v[108:109] neg_lo:[0,0,1] neg_hi:[0,0,1]
	v_pk_fma_f32 v[2:3], v[58:59], v[2:3], v[110:111] neg_lo:[0,0,1] neg_hi:[0,0,1]
	v_pk_add_f32 v[4:5], v[4:5], v[6:7] neg_lo:[0,1] neg_hi:[0,1]
	v_pk_fma_f32 v[54:55], v[60:61], v[36:37], v[104:105]
	v_pk_fma_f32 v[56:57], v[62:63], v[100:101], v[14:15]
	v_pk_fma_f32 v[58:59], v[64:65], v[102:103], v[10:11]
	v_pk_add_f32 v[10:11], v[16:17], v[20:21]
	v_mov_b32_e32 v61, v55
	v_mov_b32_e32 v63, v57
	v_mov_b32_e32 v65, v59
	v_mov_b32_e32 v7, v10
	v_mov_b32_e32 v98, v11
	v_mov_b32_e32 v60, v12
	v_mov_b32_e32 v55, v13
	v_mov_b32_e32 v62, v8
	v_mov_b32_e32 v57, v9
	v_mov_b32_e32 v64, v2
	v_mov_b32_e32 v59, v3
	v_mov_b32_e32 v20, v4
	v_mov_b32_e32 v99, v5
.LBB0_475:
	s_or_b64 exec, exec, s[16:17]
	s_and_b64 s[14:15], s[14:15], exec
	s_mov_b32 s14, 0xe085100
	s_cselect_b32 s14, s14, 0xe885100
	s_add_u32 s14, s94, s14
	s_addc_u32 s15, s95, 0
	v_lshl_add_u64 v[36:37], v[32:33], 1, s[14:15]
	v_cvt_pk_bf16_f32 v2, v60, v55
	v_cvt_pk_bf16_f32 v3, v62, v57
	v_cvt_pk_bf16_f32 v4, v64, v59
	v_cvt_pk_bf16_f32 v5, v20, v99
	global_store_dwordx4 v[36:37], v[2:5], off
	v_mov_b32_e32 v53, v52
	v_mov_b32_e32 v18, v50
	v_cvt_pk_bf16_f32 v2, v54, v61
	v_cvt_pk_bf16_f32 v3, v56, v63
	v_cvt_pk_bf16_f32 v4, v58, v65
	v_cvt_pk_bf16_f32 v5, v7, v98
	global_store_dwordx4 v[36:37], v[2:5], off offset:16
	s_nop 1
	v_mov_b64_e32 v[2:3], v[166:167]
	s_nop 0
	v_mov_b64_e32 v[4:5], v[168:169]
	s_nop 0
	v_mov_b64_e32 v[6:7], v[174:175]
	v_mov_b64_e32 v[8:9], v[176:177]
	v_mov_b64_e32 v[10:11], v[170:171]
	v_mov_b64_e32 v[12:13], v[172:173]
	v_mov_b64_e32 v[14:15], v[178:179]
	v_mov_b64_e32 v[16:17], v[180:181]
	v_mov_b32_e32 v19, v39
	v_mov_b32_e32 v39, v51
	v_mov_b32_e32 v20, v48
	v_mov_b32_e32 v21, v41
	v_mov_b32_e32 v41, v49
	v_mov_b32_e32 v48, v46
	v_mov_b32_e32 v49, v43
	v_mov_b32_e32 v43, v47
	v_mul_f32_e32 v31, v22, v52
	v_mov_b32_e32 v22, v45
	v_mul_f32_e32 v46, v44, v52
	v_pk_mul_f32 v[18:19], v[18:19], v[52:53]
	v_pk_mul_f32 v[38:39], v[38:39], v[52:53]
	v_pk_mul_f32 v[20:21], v[20:21], v[52:53]
	v_pk_mul_f32 v[40:41], v[40:41], v[52:53]
	v_pk_mul_f32 v[48:49], v[48:49], v[52:53]
	v_pk_mul_f32 v[42:43], v[42:43], v[52:53]
	v_pk_mul_f32 v[50:51], v[22:23], v[52:53]
	v_mov_b32_e32 v44, v2
	v_mov_b32_e32 v45, v7
	v_mov_b32_e32 v7, v3
	v_mov_b32_e32 v2, v4
	v_mov_b32_e32 v3, v9
	v_mov_b32_e32 v9, v5
	v_mov_b32_e32 v52, v10
	v_mov_b32_e32 v53, v15
	v_mov_b32_e32 v15, v11
	v_mul_f32_e32 v22, v31, v12
	v_mov_b32_e32 v12, v17
	v_mul_f32_e32 v5, v46, v16
	v_pk_mul_f32 v[44:45], v[18:19], v[44:45]
	v_pk_mul_f32 v[38:39], v[38:39], v[6:7]
	v_pk_mul_f32 v[46:47], v[20:21], v[2:3]
	v_pk_mul_f32 v[40:41], v[40:41], v[8:9]
	v_pk_mul_f32 v[48:49], v[48:49], v[52:53]
	v_pk_mul_f32 v[42:43], v[42:43], v[14:15]
	v_pk_mul_f32 v[50:51], v[50:51], v[12:13]
	s_and_saveexec_b64 s[14:15], s[10:11]
	s_cbranch_execz .LBB0_477
	v_mov_b32_e32 v6, v44
	v_mov_b32_e32 v7, v39
	v_mov_b32_e32 v8, v46
	v_mov_b32_e32 v9, v41
	global_store_dwordx4 v[34:35], v[6:9], off offset:64
	v_mov_b32_e32 v20, v48
	v_mov_b32_e32 v21, v43
	v_mov_b32_e32 v6, v51
	v_mov_b32_e32 v7, v38
	v_mov_b32_e32 v8, v45
	v_mov_b32_e32 v9, v40
	v_mov_b32_e32 v2, v47
	v_mov_b32_e32 v3, v42
	v_mov_b32_e32 v4, v49
	global_store_dwordx3 v[34:35], v[20:22], off offset:80
	global_store_dwordx4 v[34:35], v[6:9], off offset:92
	global_store_dwordx4 v[34:35], v[2:5], off offset:108
	global_store_dword v[34:35], v50, off offset:124
.LBB0_477:
	s_or_b64 exec, exec, s[14:15]
	s_and_saveexec_b64 s[14:15], s[42:43]
	s_cbranch_execz .LBB0_479
	v_mov_b64_e32 v[18:19], v[244:245]
	v_mov_b64_e32 v[20:21], v[246:247]
	v_mov_b64_e32 v[6:7], v[228:229]
	v_mov_b64_e32 v[8:9], v[230:231]
	v_mov_b64_e32 v[10:11], v[214:215]
	v_mov_b64_e32 v[12:13], v[216:217]
	v_mov_b64_e32 v[14:15], v[208:209]
	v_mov_b64_e32 v[16:17], v[210:211]
	v_mov_b32_e32 v58, v38
	v_mov_b32_e32 v59, v45
	v_mul_f32_e32 v4, v22, v18
	v_mov_b32_e32 v64, v7
	v_mov_b32_e32 v62, v11
	v_mov_b32_e32 v60, v15
	v_mov_b32_e32 v61, v17
	v_pk_mul_f32 v[58:59], v[58:59], v[60:61]
	v_mov_b32_e32 v60, v40
	v_mov_b32_e32 v61, v47
	v_mov_b32_e32 v63, v13
	v_pk_mul_f32 v[60:61], v[60:61], v[62:63]
	v_mov_b32_e32 v62, v42
	v_mov_b32_e32 v63, v49
	v_mov_b32_e32 v65, v9
	v_mov_b32_e32 v2, v15
	v_mov_b32_e32 v3, v16
	v_mov_b32_e32 v52, v11
	v_mov_b32_e32 v53, v12
	v_mov_b32_e32 v56, v14
	v_mov_b32_e32 v57, v17
	v_mov_b32_e32 v15, v16
	v_mov_b32_e32 v16, v10
	v_mov_b32_e32 v17, v13
	v_mov_b32_e32 v11, v12
	v_mov_b32_e32 v12, v6
	v_mov_b32_e32 v13, v9
	v_pk_mul_f32 v[62:63], v[62:63], v[64:65]
	v_pk_mul_f32 v[64:65], v[50:51], v[20:21] op_sel:[1,0] op_sel_hi:[0,1]
	v_pk_mul_f32 v[20:21], v[50:51], v[20:21]
	v_mov_b32_e32 v54, v7
	v_mov_b32_e32 v55, v8
	v_pk_mul_f32 v[56:57], v[38:39], v[56:57]
	v_mov_b32_e32 v38, v44
	v_pk_mul_f32 v[16:17], v[40:41], v[16:17]
	v_mov_b32_e32 v40, v46
	v_pk_mul_f32 v[12:13], v[42:43], v[12:13]
	v_mov_b32_e32 v42, v48
	v_mov_b32_e32 v7, v8
	v_mul_f32_e32 v8, v5, v19
	v_mul_f32_e32 v22, v22, v19
	v_mul_f32_e32 v18, v5, v18
	v_mov_b32_e32 v5, v64
	v_mov_b32_e32 v9, v65
	v_mov_b32_e32 v19, v20
	v_mov_b32_e32 v23, v21
	v_pk_fma_f32 v[14:15], v[38:39], v[14:15], v[58:59] neg_lo:[0,0,1] neg_hi:[0,0,1]
	v_pk_fma_f32 v[10:11], v[40:41], v[10:11], v[60:61] neg_lo:[0,0,1] neg_hi:[0,0,1]
	v_pk_fma_f32 v[6:7], v[42:43], v[6:7], v[62:63] neg_lo:[0,0,1] neg_hi:[0,0,1]
	v_pk_add_f32 v[8:9], v[4:5], v[8:9] neg_lo:[0,1] neg_hi:[0,1]
	v_pk_fma_f32 v[38:39], v[44:45], v[2:3], v[56:57]
	v_pk_fma_f32 v[40:41], v[46:47], v[52:53], v[16:17]
	v_pk_fma_f32 v[42:43], v[48:49], v[54:55], v[12:13]
	v_pk_add_f32 v[2:3], v[18:19], v[22:23]
	v_mov_b32_e32 v45, v39
	v_mov_b32_e32 v47, v41
	v_mov_b32_e32 v49, v43
	v_mov_b32_e32 v5, v2
	v_mov_b32_e32 v50, v3
	v_mov_b32_e32 v44, v14
	v_mov_b32_e32 v39, v15
	v_mov_b32_e32 v46, v10
	v_mov_b32_e32 v41, v11
	v_mov_b32_e32 v48, v6
	v_mov_b32_e32 v43, v7
	v_mov_b32_e32 v22, v8
	v_mov_b32_e32 v51, v9
.LBB0_479:
	s_or_b64 exec, exec, s[14:15]
	v_cvt_pk_bf16_f32 v6, v44, v39
	v_cvt_pk_bf16_f32 v7, v46, v41
	v_cvt_pk_bf16_f32 v8, v48, v43
	v_cvt_pk_bf16_f32 v9, v22, v51
	v_cvt_pk_bf16_f32 v2, v38, v45
	v_cvt_pk_bf16_f32 v3, v40, v47
	v_cvt_pk_bf16_f32 v4, v42, v49
	v_cvt_pk_bf16_f32 v5, v5, v50
	global_store_dwordx4 v[36:37], v[6:9], off offset:32
	global_store_dwordx4 v[36:37], v[2:5], off offset:48
	ds_read2_b32 v[14:15], v155 offset0:38 offset1:39
	ds_read2_b32 v[16:17], v155 offset0:46 offset1:47
	ds_read2_b32 v[22:23], v155 offset0:54 offset1:55
	ds_read2_b32 v[50:51], v155 offset0:48 offset1:49
	ds_read2_b32 v[48:49], v155 offset0:50 offset1:51
	ds_read2_b32 v[110:111], v155 offset0:32 offset1:33
	ds_read2_b32 v[18:19], v155 offset0:40 offset1:41
	ds_read2_b32 v[38:39], v155 offset0:56 offset1:57
	ds_read2_b32 v[40:41], v155 offset0:58 offset1:59
	ds_read2_b32 v[42:43], v155 offset0:60 offset1:61
	ds_read2_b32 v[46:47], v155 offset0:52 offset1:53
	ds_read2_b32 v[44:45], v155 offset0:62 offset1:63
	v_mov_b64_e32 v[2:3], v[142:143]
	v_mov_b64_e32 v[4:5], v[144:145]
	v_mov_b64_e32 v[6:7], v[162:163]
	v_mov_b64_e32 v[8:9], v[164:165]
	v_mov_b64_e32 v[10:11], v[158:159]
	v_mov_b64_e32 v[12:13], v[160:161]
	v_mov_b64_e32 v[106:107], v[124:125]
	v_mov_b64_e32 v[108:109], v[126:127]
	s_waitcnt lgkmcnt(6)
	v_pk_mul_f32 v[100:101], v[110:111], v[110:111]
	s_waitcnt lgkmcnt(5)
	v_pk_mul_f32 v[98:99], v[18:19], v[18:19]
	v_mov_b32_e32 v102, v110
	v_mov_b32_e32 v103, v19
	v_mov_b32_e32 v19, v111
	v_add_f32_e32 v31, v100, v101
	v_pk_mul_f32 v[60:61], v[50:51], v[50:51]
	v_pk_mul_f32 v[62:63], v[48:49], v[48:49]
	s_waitcnt lgkmcnt(1)
	v_pk_mul_f32 v[64:65], v[46:47], v[46:47]
	v_pk_mul_f32 v[52:53], v[22:23], v[22:23]
	v_pk_mul_f32 v[54:55], v[38:39], v[38:39]
	v_pk_mul_f32 v[56:57], v[40:41], v[40:41]
	v_pk_mul_f32 v[58:59], v[42:43], v[42:43]
	s_waitcnt lgkmcnt(0)
	v_pk_mul_f32 v[20:21], v[44:45], v[44:45]
	ds_read2_b32 v[112:113], v155 offset0:42 offset1:43
	ds_read2_b32 v[120:121], v155 offset0:44 offset1:45
	s_waitcnt lgkmcnt(1)
	v_pk_mul_f32 v[114:115], v[112:113], v[112:113]
	v_mov_b32_e32 v117, v113
	s_waitcnt lgkmcnt(0)
	v_pk_mul_f32 v[122:123], v[120:121], v[120:121]
	v_mov_b32_e32 v105, v11
	v_mov_b32_e32 v104, v106
	v_mov_b32_e32 v11, v107
	ds_read2_b32 v[106:107], v155 offset0:34 offset1:35
	v_mov_b32_e32 v118, v108
	v_mov_b32_e32 v119, v13
	v_mov_b32_e32 v13, v109
	s_waitcnt lgkmcnt(0)
	v_pk_mul_f32 v[110:111], v[106:107], v[106:107]
	v_mov_b32_e32 v116, v106
	v_mov_b32_e32 v113, v107
	ds_read2_b32 v[106:107], v155 offset0:36 offset1:37
	v_add_f32_e32 v31, v31, v110
	v_add_f32_e32 v31, v31, v111
	s_waitcnt lgkmcnt(0)
	v_pk_mul_f32 v[108:109], v[106:107], v[106:107]
	s_nop 0
	v_add_f32_e32 v31, v31, v108
	v_add_f32_e32 v31, v31, v109
	v_fmac_f32_e32 v31, v14, v14
	v_fmac_f32_e32 v31, v15, v15
	v_add_f32_e32 v31, v31, v98
	v_add_f32_e32 v31, v31, v99
	v_add_f32_e32 v31, v31, v114
	v_add_f32_e32 v31, v31, v115
	v_add_f32_e32 v31, v31, v122
	v_add_f32_e32 v31, v31, v123
	v_fmac_f32_e32 v31, v16, v16
	v_fmac_f32_e32 v31, v17, v17
	v_add_f32_e32 v31, v31, v60
	v_add_f32_e32 v31, v31, v61
	v_add_f32_e32 v31, v31, v62
	v_add_f32_e32 v31, v31, v63
	v_add_f32_e32 v31, v31, v64
	v_add_f32_e32 v31, v31, v65
	v_add_f32_e32 v31, v31, v52
	v_add_f32_e32 v31, v31, v53
	v_add_f32_e32 v31, v31, v54
	v_add_f32_e32 v31, v31, v55
	v_add_f32_e32 v31, v31, v56
	v_add_f32_e32 v31, v31, v57
	v_add_f32_e32 v31, v31, v58
	v_add_f32_e32 v31, v31, v59
	v_add_f32_e32 v20, v31, v20
	v_add_f32_e32 v20, v20, v21
	v_fmamk_f32 v20, v20, 0x3d000000, v213
	v_cmp_gt_f32_e32 vcc, s54, v20
	v_mul_f32_e32 v21, 0x4b800000, v20
	s_nop 0
	v_cndmask_b32_e32 v20, v20, v21, vcc
	v_rsq_f32_e32 v20, v20
	s_nop 0
	v_mul_f32_e32 v21, 0x45800000, v20
	v_cndmask_b32_e32 v52, v20, v21, vcc
	v_pk_mul_f32 v[18:19], v[18:19], v[52:53] op_sel_hi:[1,0]
	v_pk_mul_f32 v[20:21], v[102:103], v[52:53] op_sel_hi:[1,0]
	v_pk_mul_f32 v[54:55], v[10:11], v[18:19]
	v_pk_mul_f32 v[10:11], v[116:117], v[52:53] op_sel_hi:[1,0]
	v_pk_mul_f32 v[60:61], v[104:105], v[20:21]
	v_pk_mul_f32 v[62:63], v[118:119], v[10:11]
	v_pk_mul_f32 v[10:11], v[112:113], v[52:53] op_sel_hi:[1,0]
	s_nop 0
	v_pk_mul_f32 v[56:57], v[12:13], v[10:11]
	v_mov_b32_e32 v10, v106
	v_mov_b32_e32 v11, v121
	v_pk_mul_f32 v[10:11], v[10:11], v[52:53] op_sel_hi:[1,0]
	v_mov_b32_e32 v12, v2
	v_mov_b32_e32 v13, v7
	v_mov_b32_e32 v121, v107
	v_mul_f32_e32 v2, v14, v52
	v_pk_mul_f32 v[64:65], v[12:13], v[10:11]
	v_pk_mul_f32 v[10:11], v[120:121], v[52:53] op_sel_hi:[1,0]
	v_mov_b32_e32 v7, v3
	v_mul_f32_e32 v20, v2, v4
	v_mul_f32_e32 v2, v16, v52
	v_mov_b32_e32 v14, v17
	v_pk_mul_f32 v[58:59], v[10:11], v[6:7]
	v_mul_f32_e32 v7, v2, v8
	v_pk_mul_f32 v[2:3], v[14:15], v[52:53] op_sel_hi:[1,0]
	v_mov_b32_e32 v4, v9
	v_pk_mul_f32 v[98:99], v[2:3], v[4:5]
	s_and_saveexec_b64 s[14:15], s[10:11]
	s_cbranch_execz .LBB0_481
	v_mov_b32_e32 v2, v60
	v_mov_b32_e32 v3, v55
	v_mov_b32_e32 v4, v62
	v_mov_b32_e32 v5, v57
	global_store_dwordx4 v[34:35], v[2:5], off offset:128
	v_mov_b32_e32 v18, v64
	v_mov_b32_e32 v19, v59
	v_mov_b32_e32 v2, v99
	v_mov_b32_e32 v3, v54
	v_mov_b32_e32 v4, v61
	v_mov_b32_e32 v5, v56
	global_store_dwordx4 v[34:35], v[2:5], off offset:156
	v_mov_b32_e32 v6, v65
	global_store_dwordx3 v[34:35], v[18:20], off offset:144
	v_mov_b32_e32 v4, v63
	v_mov_b32_e32 v5, v58
	global_store_dwordx4 v[34:35], v[4:7], off offset:172
	global_store_dword v[34:35], v98, off offset:188
.LBB0_481:
	s_or_b64 exec, exec, s[14:15]
	s_and_saveexec_b64 s[14:15], s[42:43]
	s_cbranch_execz .LBB0_483
	v_mov_b64_e32 v[16:17], v[194:195]
	v_mov_b64_e32 v[18:19], v[196:197]
	v_mov_b64_e32 v[2:3], v[190:191]
	v_mov_b64_e32 v[4:5], v[192:193]
	v_mov_b64_e32 v[8:9], v[186:187]
	v_mov_b64_e32 v[10:11], v[188:189]
	v_mov_b64_e32 v[12:13], v[182:183]
	v_mov_b64_e32 v[14:15], v[184:185]
	v_mov_b32_e32 v108, v54
	v_mov_b32_e32 v109, v61
	v_mul_f32_e32 v6, v7, v17
	v_mov_b32_e32 v114, v3
	v_mov_b32_e32 v112, v9
	v_mov_b32_e32 v110, v13
	v_mov_b32_e32 v111, v15
	v_pk_mul_f32 v[108:109], v[108:109], v[110:111]
	v_mov_b32_e32 v110, v56
	v_mov_b32_e32 v111, v63
	v_mov_b32_e32 v113, v11
	v_pk_mul_f32 v[110:111], v[110:111], v[112:113]
	v_mov_b32_e32 v112, v58
	v_mov_b32_e32 v113, v65
	v_mov_b32_e32 v115, v5
	v_mov_b32_e32 v100, v13
	v_mov_b32_e32 v101, v14
	v_mov_b32_e32 v102, v9
	v_mov_b32_e32 v103, v10
	v_mov_b32_e32 v106, v12
	v_mov_b32_e32 v107, v15
	v_mov_b32_e32 v13, v14
	v_mov_b32_e32 v14, v8
	v_mov_b32_e32 v15, v11
	v_mov_b32_e32 v9, v10
	v_mov_b32_e32 v10, v2
	v_mov_b32_e32 v11, v5
	v_pk_mul_f32 v[112:113], v[112:113], v[114:115]
	v_pk_mul_f32 v[114:115], v[98:99], v[18:19] op_sel:[1,0] op_sel_hi:[0,1]
	v_pk_mul_f32 v[18:19], v[98:99], v[18:19]
	v_mov_b32_e32 v104, v3
	v_mov_b32_e32 v105, v4
	v_pk_mul_f32 v[106:107], v[54:55], v[106:107]
	v_mov_b32_e32 v54, v60
	v_pk_mul_f32 v[14:15], v[56:57], v[14:15]
	v_mov_b32_e32 v56, v62
	v_pk_mul_f32 v[10:11], v[58:59], v[10:11]
	v_mov_b32_e32 v58, v64
	v_mov_b32_e32 v3, v4
	v_mul_f32_e32 v4, v20, v16
	v_mul_f32_e32 v20, v20, v17
	v_mul_f32_e32 v16, v7, v16
	v_mov_b32_e32 v5, v114
	v_mov_b32_e32 v7, v115
	v_mov_b32_e32 v17, v18
	v_mov_b32_e32 v21, v19
	v_pk_fma_f32 v[12:13], v[54:55], v[12:13], v[108:109] neg_lo:[0,0,1] neg_hi:[0,0,1]
	v_pk_fma_f32 v[8:9], v[56:57], v[8:9], v[110:111] neg_lo:[0,0,1] neg_hi:[0,0,1]
	v_pk_fma_f32 v[2:3], v[58:59], v[2:3], v[112:113] neg_lo:[0,0,1] neg_hi:[0,0,1]
	v_pk_add_f32 v[4:5], v[4:5], v[6:7] neg_lo:[0,1] neg_hi:[0,1]
	v_pk_fma_f32 v[54:55], v[60:61], v[100:101], v[106:107]
	v_pk_fma_f32 v[56:57], v[62:63], v[102:103], v[14:15]
	v_pk_fma_f32 v[58:59], v[64:65], v[104:105], v[10:11]
	v_pk_add_f32 v[10:11], v[16:17], v[20:21]
	v_mov_b32_e32 v61, v55
	v_mov_b32_e32 v63, v57
	v_mov_b32_e32 v65, v59
	v_mov_b32_e32 v7, v10
	v_mov_b32_e32 v98, v11
	v_mov_b32_e32 v60, v12
	v_mov_b32_e32 v55, v13
	v_mov_b32_e32 v62, v8
	v_mov_b32_e32 v57, v9
	v_mov_b32_e32 v64, v2
	v_mov_b32_e32 v59, v3
	v_mov_b32_e32 v20, v4
	v_mov_b32_e32 v99, v5
.LBB0_483:
	s_or_b64 exec, exec, s[14:15]
	v_cvt_pk_bf16_f32 v2, v60, v55
	v_cvt_pk_bf16_f32 v3, v62, v57
	v_cvt_pk_bf16_f32 v4, v64, v59
	v_cvt_pk_bf16_f32 v5, v20, v99
	global_store_dwordx4 v[36:37], v[2:5], off offset:64
	v_mov_b32_e32 v53, v52
	v_mov_b32_e32 v18, v50
	v_cvt_pk_bf16_f32 v2, v54, v61
	v_cvt_pk_bf16_f32 v3, v56, v63
	v_cvt_pk_bf16_f32 v4, v58, v65
	v_cvt_pk_bf16_f32 v5, v7, v98
	global_store_dwordx4 v[36:37], v[2:5], off offset:80
	s_nop 1
	v_mov_b64_e32 v[2:3], v[166:167]
	s_nop 0
	v_mov_b64_e32 v[4:5], v[168:169]
	s_nop 0
	v_mov_b64_e32 v[6:7], v[174:175]
	v_mov_b64_e32 v[8:9], v[176:177]
	v_mov_b64_e32 v[10:11], v[170:171]
	v_mov_b64_e32 v[12:13], v[172:173]
	v_mov_b64_e32 v[14:15], v[178:179]
	v_mov_b64_e32 v[16:17], v[180:181]
	v_mov_b32_e32 v19, v39
	v_mov_b32_e32 v39, v51
	v_mov_b32_e32 v20, v48
	v_mov_b32_e32 v21, v41
	v_mov_b32_e32 v41, v49
	v_mov_b32_e32 v48, v46
	v_mov_b32_e32 v49, v43
	v_mov_b32_e32 v43, v47
	v_mul_f32_e32 v27, v22, v52
	v_mov_b32_e32 v22, v45
	v_mul_f32_e32 v31, v44, v52
	v_pk_mul_f32 v[18:19], v[18:19], v[52:53]
	v_pk_mul_f32 v[38:39], v[38:39], v[52:53]
	v_pk_mul_f32 v[20:21], v[20:21], v[52:53]
	v_pk_mul_f32 v[40:41], v[40:41], v[52:53]
	v_pk_mul_f32 v[48:49], v[48:49], v[52:53]
	v_pk_mul_f32 v[42:43], v[42:43], v[52:53]
	v_pk_mul_f32 v[50:51], v[22:23], v[52:53]
	v_mov_b32_e32 v44, v2
	v_mov_b32_e32 v45, v7
	v_mov_b32_e32 v7, v3
	v_mov_b32_e32 v2, v4
	v_mov_b32_e32 v3, v9
	v_mov_b32_e32 v9, v5
	v_mov_b32_e32 v52, v10
	v_mov_b32_e32 v53, v15
	v_mov_b32_e32 v15, v11
	v_mul_f32_e32 v22, v27, v12
	v_mov_b32_e32 v12, v17
	v_mul_f32_e32 v5, v31, v16
	v_pk_mul_f32 v[44:45], v[18:19], v[44:45]
	v_pk_mul_f32 v[38:39], v[38:39], v[6:7]
	v_pk_mul_f32 v[46:47], v[20:21], v[2:3]
	v_pk_mul_f32 v[40:41], v[40:41], v[8:9]
	v_pk_mul_f32 v[48:49], v[48:49], v[52:53]
	v_pk_mul_f32 v[42:43], v[42:43], v[14:15]
	v_pk_mul_f32 v[50:51], v[50:51], v[12:13]
	s_and_saveexec_b64 s[12:13], s[10:11]
	s_cbranch_execz .LBB0_485
	v_mov_b32_e32 v6, v44
	v_mov_b32_e32 v7, v39
	v_mov_b32_e32 v8, v46
	v_mov_b32_e32 v9, v41
	global_store_dwordx4 v[34:35], v[6:9], off offset:192
	v_mov_b32_e32 v20, v48
	v_mov_b32_e32 v21, v43
	v_mov_b32_e32 v6, v51
	v_mov_b32_e32 v7, v38
	v_mov_b32_e32 v8, v45
	v_mov_b32_e32 v9, v40
	v_mov_b32_e32 v2, v47
	v_mov_b32_e32 v3, v42
	v_mov_b32_e32 v4, v49
	global_store_dwordx3 v[34:35], v[20:22], off offset:208
	global_store_dwordx4 v[34:35], v[6:9], off offset:220
	global_store_dwordx4 v[34:35], v[2:5], off offset:236
	global_store_dword v[34:35], v50, off offset:252
.LBB0_485:
	s_or_b64 exec, exec, s[12:13]
	s_and_saveexec_b64 s[10:11], s[42:43]
	s_cbranch_execz .LBB0_487
	v_mov_b64_e32 v[18:19], v[244:245]
	v_mov_b64_e32 v[20:21], v[246:247]
	v_mov_b64_e32 v[6:7], v[228:229]
	v_mov_b64_e32 v[8:9], v[230:231]
	v_mov_b64_e32 v[10:11], v[214:215]
	v_mov_b64_e32 v[12:13], v[216:217]
	v_mov_b64_e32 v[14:15], v[208:209]
	v_mov_b64_e32 v[16:17], v[210:211]
	v_mov_b32_e32 v56, v38
	v_mov_b32_e32 v57, v45
	v_mul_f32_e32 v4, v22, v18
	v_mov_b32_e32 v62, v7
	v_mov_b32_e32 v60, v11
	v_mov_b32_e32 v58, v15
	v_mov_b32_e32 v59, v17
	v_pk_mul_f32 v[56:57], v[56:57], v[58:59]
	v_mov_b32_e32 v58, v40
	v_mov_b32_e32 v59, v47
	v_mov_b32_e32 v61, v13
	v_pk_mul_f32 v[58:59], v[58:59], v[60:61]
	v_mov_b32_e32 v60, v42
	v_mov_b32_e32 v61, v49
	v_mov_b32_e32 v63, v9
	v_mov_b32_e32 v2, v15
	v_mov_b32_e32 v3, v16
	v_mov_b32_e32 v34, v11
	v_mov_b32_e32 v35, v12
	v_mov_b32_e32 v54, v14
	v_mov_b32_e32 v55, v17
	v_mov_b32_e32 v15, v16
	v_mov_b32_e32 v16, v10
	v_mov_b32_e32 v17, v13
	v_mov_b32_e32 v11, v12
	v_mov_b32_e32 v12, v6
	v_mov_b32_e32 v13, v9
	v_pk_mul_f32 v[60:61], v[60:61], v[62:63]
	v_pk_mul_f32 v[62:63], v[50:51], v[20:21] op_sel:[1,0] op_sel_hi:[0,1]
	v_pk_mul_f32 v[20:21], v[50:51], v[20:21]
	v_mov_b32_e32 v52, v7
	v_mov_b32_e32 v53, v8
	v_pk_mul_f32 v[54:55], v[38:39], v[54:55]
	v_mov_b32_e32 v38, v44
	v_pk_mul_f32 v[16:17], v[40:41], v[16:17]
	v_mov_b32_e32 v40, v46
	v_pk_mul_f32 v[12:13], v[42:43], v[12:13]
	v_mov_b32_e32 v42, v48
	v_mov_b32_e32 v7, v8
	v_mul_f32_e32 v8, v5, v19
	v_mul_f32_e32 v22, v22, v19
	v_mul_f32_e32 v18, v5, v18
	v_mov_b32_e32 v5, v62
	v_mov_b32_e32 v9, v63
	v_mov_b32_e32 v19, v20
	v_mov_b32_e32 v23, v21
	v_pk_fma_f32 v[14:15], v[38:39], v[14:15], v[56:57] neg_lo:[0,0,1] neg_hi:[0,0,1]
	v_pk_fma_f32 v[10:11], v[40:41], v[10:11], v[58:59] neg_lo:[0,0,1] neg_hi:[0,0,1]
	v_pk_fma_f32 v[6:7], v[42:43], v[6:7], v[60:61] neg_lo:[0,0,1] neg_hi:[0,0,1]
	v_pk_add_f32 v[8:9], v[4:5], v[8:9] neg_lo:[0,1] neg_hi:[0,1]
	v_pk_fma_f32 v[38:39], v[44:45], v[2:3], v[54:55]
	v_pk_fma_f32 v[40:41], v[46:47], v[34:35], v[16:17]
	v_pk_fma_f32 v[42:43], v[48:49], v[52:53], v[12:13]
	v_pk_add_f32 v[2:3], v[18:19], v[22:23]
	v_mov_b32_e32 v45, v39
	v_mov_b32_e32 v47, v41
	v_mov_b32_e32 v49, v43
	v_mov_b32_e32 v5, v2
	v_mov_b32_e32 v50, v3
	v_mov_b32_e32 v44, v14
	v_mov_b32_e32 v39, v15
	v_mov_b32_e32 v46, v10
	v_mov_b32_e32 v41, v11
	v_mov_b32_e32 v48, v6
	v_mov_b32_e32 v43, v7
	v_mov_b32_e32 v22, v8
	v_mov_b32_e32 v51, v9

.LBB0_488:
	s_and_b64 vcc, exec, s[10:11]
	s_cbranch_vccz .LBB0_506
	v_mad_i64_i32 v[2:3], s[10:11], v28, v29, 0
	s_cmp_eq_u32 s19, 4
	s_mov_b32 s10, 0xd885100
	s_cselect_b32 s10, s10, 0xf085100
	s_brev_b32 s11, 32
	s_cselect_b32 s12, s11, 0x6000000
	s_add_u32 s10, s94, s10
	s_addc_u32 s11, s95, 0
	v_lshlrev_b32_e32 v4, 1, v30
	v_mov_b32_e32 v5, v1
	v_readlane_b32 s72, v253, 51
	v_lshl_add_u64 v[4:5], s[10:11], 0, v[4:5]
	v_lshlrev_b64 v[2:3], 7, v[2:3]
	v_readlane_b32 s84, v253, 63
	v_readlane_b32 s85, v254, 0
	v_lshl_add_u64 v[2:3], v[4:5], 0, v[2:3]
	v_lshlrev_b32_e32 v4, 1, v0
	v_mov_b32_e32 v5, v1
	v_readlane_b32 s86, v254, 1
	v_readlane_b32 s87, v254, 2
	s_mov_b64 s[24:25], s[84:85]
	v_ashrrev_i32_e32 v27, 31, v26
	v_lshl_add_u64 v[14:15], v[2:3], 0, v[4:5]
	s_mov_b64 s[26:27], s[86:87]
	v_lshl_add_u64 v[2:3], v[26:27], 4, s[0:1]
	s_add_u32 s10, s26, s12
	v_or_b32_e32 v2, v2, v25
	s_addc_u32 s11, s27, 0
	v_lshlrev_b64 v[2:3], 16, v[2:3]
	v_lshl_add_u64 v[6:7], s[10:11], 0, v[2:3]
	ds_read2_b32 v[2:3], v155 offset1:1
	v_lshlrev_b32_e32 v4, 8, v0
	v_lshl_add_u64 v[10:11], v[6:7], 0, v[4:5]
	ds_read2_b32 v[4:5], v155 offset0:2 offset1:3
	ds_read2_b32 v[6:7], v155 offset0:4 offset1:5
	ds_read2_b32 v[8:9], v155 offset0:6 offset1:7
	ds_read2_b32 v[42:43], v155 offset0:8 offset1:9
	ds_read2_b32 v[44:45], v155 offset0:10 offset1:11
	ds_read2_b32 v[46:47], v155 offset0:12 offset1:13
	ds_read2_b32 v[48:49], v155 offset0:14 offset1:15
	ds_read2_b32 v[50:51], v155 offset0:16 offset1:17
	ds_read2_b32 v[52:53], v155 offset0:18 offset1:19
	ds_read2_b32 v[54:55], v155 offset0:20 offset1:21
	ds_read2_b32 v[56:57], v155 offset0:22 offset1:23
	ds_read2_b32 v[58:59], v155 offset0:24 offset1:25
	ds_read2_b32 v[60:61], v155 offset0:26 offset1:27
	ds_read2_b32 v[62:63], v155 offset0:28 offset1:29
	ds_read2_b32 v[64:65], v155 offset0:30 offset1:31
	ds_read2_b32 v[98:99], v155 offset0:32 offset1:33
	ds_read2_b32 v[100:101], v155 offset0:34 offset1:35
	ds_read2_b32 v[102:103], v155 offset0:36 offset1:37
	ds_read2_b32 v[104:105], v155 offset0:38 offset1:39
	ds_read2_b32 v[106:107], v155 offset0:40 offset1:41
	ds_read2_b32 v[108:109], v155 offset0:42 offset1:43
	ds_read2_b32 v[110:111], v155 offset0:44 offset1:45
	ds_read2_b32 v[112:113], v155 offset0:46 offset1:47
	ds_read2_b32 v[114:115], v155 offset0:48 offset1:49
	ds_read2_b32 v[116:117], v155 offset0:50 offset1:51
	ds_read2_b32 v[118:119], v155 offset0:52 offset1:53
	ds_read2_b32 v[120:121], v155 offset0:54 offset1:55
	ds_read2_b32 v[122:123], v155 offset0:56 offset1:57
	ds_read2_b32 v[124:125], v155 offset0:58 offset1:59
	ds_read2_b32 v[126:127], v155 offset0:60 offset1:61
	ds_read2_b32 v[128:129], v155 offset0:62 offset1:63
	v_mov_b32_e32 v13, v1
	s_waitcnt lgkmcnt(3)
	v_bfe_u32 v12, v2, 16, 1
	v_add3_u32 v12, v2, v12, s37
	global_store_short_d16_hi v[14:15], v12, off
	v_bfe_u32 v12, v3, 16, 1
	v_add3_u32 v16, v3, v12, s37
	v_lshlrev_b32_e32 v12, 1, v28
	v_lshl_add_u64 v[14:15], v[14:15], 0, v[12:13]
	global_store_short_d16_hi v[14:15], v16, off
	s_waitcnt lgkmcnt(2)
	v_bfe_u32 v16, v4, 16, 1
	v_lshl_add_u64 v[14:15], v[14:15], 0, v[12:13]
	v_add3_u32 v16, v4, v16, s37
	global_store_short_d16_hi v[14:15], v16, off
	v_bfe_u32 v16, v5, 16, 1
	v_add3_u32 v16, v5, v16, s37
	v_lshl_add_u64 v[14:15], v[14:15], 0, v[12:13]
	global_store_short_d16_hi v[14:15], v16, off
	s_waitcnt lgkmcnt(1)
	v_bfe_u32 v16, v6, 16, 1
	v_lshl_add_u64 v[14:15], v[14:15], 0, v[12:13]
	v_add3_u32 v16, v6, v16, s37
	global_store_short_d16_hi v[14:15], v16, off
	v_bfe_u32 v16, v7, 16, 1
	v_add3_u32 v16, v7, v16, s37
	v_lshl_add_u64 v[14:15], v[14:15], 0, v[12:13]
	global_store_short_d16_hi v[14:15], v16, off
	s_waitcnt lgkmcnt(0)
	v_bfe_u32 v16, v8, 16, 1
	v_lshl_add_u64 v[14:15], v[14:15], 0, v[12:13]
	v_add3_u32 v16, v8, v16, s37
	global_store_short_d16_hi v[14:15], v16, off
	v_bfe_u32 v16, v9, 16, 1
	v_add3_u32 v16, v9, v16, s37
	v_lshl_add_u64 v[14:15], v[14:15], 0, v[12:13]
	v_readlane_b32 s73, v253, 52
	v_readlane_b32 s74, v253, 53
	v_readlane_b32 s75, v253, 54
	v_readlane_b32 s76, v253, 55
	v_readlane_b32 s77, v253, 56
	v_readlane_b32 s78, v253, 57
	v_readlane_b32 s79, v253, 58
	v_readlane_b32 s80, v253, 59
	v_readlane_b32 s81, v253, 60
	v_readlane_b32 s82, v253, 61
	v_readlane_b32 s83, v253, 62
	global_store_short_d16_hi v[14:15], v16, off
	s_and_saveexec_b64 s[10:11], s[40:41]
	s_cbranch_execz .LBB0_491
	v_add_co_u32_e32 v16, vcc, 0x40000, v10
	s_nop 1
	v_addc_co_u32_e32 v17, vcc, 0, v11, vcc
	global_store_dwordx4 v[16:17], v[2:5], off
	global_store_dwordx4 v[16:17], v[6:9], off offset:16
.LBB0_491:
	s_or_b64 exec, exec, s[10:11]
	v_mov_b64_e32 v[2:3], v[42:43]
	v_lshl_add_u64 v[14:15], v[14:15], 0, v[12:13]
	v_mov_b64_e32 v[4:5], v[44:45]
	v_mov_b64_e32 v[6:7], v[46:47]
	v_mov_b64_e32 v[8:9], v[48:49]
	s_waitcnt lgkmcnt(3)
	v_bfe_u32 v16, v2, 16, 1
	v_add3_u32 v16, v2, v16, s37
	global_store_short_d16_hi v[14:15], v16, off
	v_bfe_u32 v16, v3, 16, 1
	v_add3_u32 v16, v3, v16, s37
	v_lshl_add_u64 v[14:15], v[14:15], 0, v[12:13]
	global_store_short_d16_hi v[14:15], v16, off
	s_waitcnt lgkmcnt(2)
	v_bfe_u32 v16, v4, 16, 1
	v_lshl_add_u64 v[14:15], v[14:15], 0, v[12:13]
	v_add3_u32 v16, v4, v16, s37
	global_store_short_d16_hi v[14:15], v16, off
	v_bfe_u32 v16, v5, 16, 1
	v_add3_u32 v16, v5, v16, s37
	v_lshl_add_u64 v[14:15], v[14:15], 0, v[12:13]
	global_store_short_d16_hi v[14:15], v16, off
	s_waitcnt lgkmcnt(1)
	v_bfe_u32 v16, v6, 16, 1
	v_lshl_add_u64 v[14:15], v[14:15], 0, v[12:13]
	v_add3_u32 v16, v6, v16, s37
	global_store_short_d16_hi v[14:15], v16, off
	v_bfe_u32 v16, v7, 16, 1
	v_add3_u32 v16, v7, v16, s37
	v_lshl_add_u64 v[14:15], v[14:15], 0, v[12:13]
	global_store_short_d16_hi v[14:15], v16, off
	s_waitcnt lgkmcnt(0)
	v_bfe_u32 v16, v8, 16, 1
	v_lshl_add_u64 v[14:15], v[14:15], 0, v[12:13]
	v_add3_u32 v16, v8, v16, s37
	global_store_short_d16_hi v[14:15], v16, off
	v_bfe_u32 v16, v9, 16, 1
	v_add3_u32 v16, v9, v16, s37
	v_lshl_add_u64 v[14:15], v[14:15], 0, v[12:13]
	global_store_short_d16_hi v[14:15], v16, off
	s_and_saveexec_b64 s[10:11], s[40:41]
	s_cbranch_execz .LBB0_493
	v_add_co_u32_e32 v16, vcc, 0x40000, v10
	s_nop 1
	v_addc_co_u32_e32 v17, vcc, 0, v11, vcc
	global_store_dwordx4 v[16:17], v[2:5], off offset:32
	global_store_dwordx4 v[16:17], v[6:9], off offset:48
.LBB0_493:
	s_or_b64 exec, exec, s[10:11]
	v_mov_b64_e32 v[2:3], v[50:51]
	v_lshl_add_u64 v[14:15], v[14:15], 0, v[12:13]
	v_mov_b64_e32 v[4:5], v[52:53]
	v_mov_b64_e32 v[6:7], v[54:55]
	v_mov_b64_e32 v[8:9], v[56:57]
	s_waitcnt lgkmcnt(3)
	v_bfe_u32 v16, v2, 16, 1
	v_add3_u32 v16, v2, v16, s37
	global_store_short_d16_hi v[14:15], v16, off
	v_bfe_u32 v16, v3, 16, 1
	v_add3_u32 v16, v3, v16, s37
	v_lshl_add_u64 v[14:15], v[14:15], 0, v[12:13]
	global_store_short_d16_hi v[14:15], v16, off
	s_waitcnt lgkmcnt(2)
	v_bfe_u32 v16, v4, 16, 1
	v_lshl_add_u64 v[14:15], v[14:15], 0, v[12:13]
	v_add3_u32 v16, v4, v16, s37
	global_store_short_d16_hi v[14:15], v16, off
	v_bfe_u32 v16, v5, 16, 1
	v_add3_u32 v16, v5, v16, s37
	v_lshl_add_u64 v[14:15], v[14:15], 0, v[12:13]
	global_store_short_d16_hi v[14:15], v16, off
	s_waitcnt lgkmcnt(1)
	v_bfe_u32 v16, v6, 16, 1
	v_lshl_add_u64 v[14:15], v[14:15], 0, v[12:13]
	v_add3_u32 v16, v6, v16, s37
	global_store_short_d16_hi v[14:15], v16, off
	v_bfe_u32 v16, v7, 16, 1
	v_add3_u32 v16, v7, v16, s37
	v_lshl_add_u64 v[14:15], v[14:15], 0, v[12:13]
	global_store_short_d16_hi v[14:15], v16, off
	s_waitcnt lgkmcnt(0)
	v_bfe_u32 v16, v8, 16, 1
	v_lshl_add_u64 v[14:15], v[14:15], 0, v[12:13]
	v_add3_u32 v16, v8, v16, s37
	global_store_short_d16_hi v[14:15], v16, off
	v_bfe_u32 v16, v9, 16, 1
	v_add3_u32 v16, v9, v16, s37
	v_lshl_add_u64 v[14:15], v[14:15], 0, v[12:13]
	global_store_short_d16_hi v[14:15], v16, off
	s_and_saveexec_b64 s[10:11], s[40:41]
	s_cbranch_execz .LBB0_495
	v_add_co_u32_e32 v16, vcc, 0x40000, v10
	s_nop 1
	v_addc_co_u32_e32 v17, vcc, 0, v11, vcc
	global_store_dwordx4 v[16:17], v[2:5], off offset:64
	global_store_dwordx4 v[16:17], v[6:9], off offset:80
.LBB0_495:
	s_or_b64 exec, exec, s[10:11]
	v_mov_b64_e32 v[2:3], v[58:59]
	v_lshl_add_u64 v[14:15], v[14:15], 0, v[12:13]
	v_mov_b64_e32 v[4:5], v[60:61]
	v_mov_b64_e32 v[6:7], v[62:63]
	v_mov_b64_e32 v[8:9], v[64:65]
	s_waitcnt lgkmcnt(3)
	v_bfe_u32 v16, v2, 16, 1
	v_add3_u32 v16, v2, v16, s37
	global_store_short_d16_hi v[14:15], v16, off
	v_bfe_u32 v16, v3, 16, 1
	v_add3_u32 v16, v3, v16, s37
	v_lshl_add_u64 v[14:15], v[14:15], 0, v[12:13]
	global_store_short_d16_hi v[14:15], v16, off
	s_waitcnt lgkmcnt(2)
	v_bfe_u32 v16, v4, 16, 1
	v_lshl_add_u64 v[14:15], v[14:15], 0, v[12:13]
	v_add3_u32 v16, v4, v16, s37
	global_store_short_d16_hi v[14:15], v16, off
	v_bfe_u32 v16, v5, 16, 1
	v_add3_u32 v16, v5, v16, s37
	v_lshl_add_u64 v[14:15], v[14:15], 0, v[12:13]
	global_store_short_d16_hi v[14:15], v16, off
	s_waitcnt lgkmcnt(1)
	v_bfe_u32 v16, v6, 16, 1
	v_lshl_add_u64 v[14:15], v[14:15], 0, v[12:13]
	v_add3_u32 v16, v6, v16, s37
	global_store_short_d16_hi v[14:15], v16, off
	v_bfe_u32 v16, v7, 16, 1
	v_add3_u32 v16, v7, v16, s37
	v_lshl_add_u64 v[14:15], v[14:15], 0, v[12:13]
	global_store_short_d16_hi v[14:15], v16, off
	s_waitcnt lgkmcnt(0)
	v_bfe_u32 v16, v8, 16, 1
	v_lshl_add_u64 v[14:15], v[14:15], 0, v[12:13]
	v_add3_u32 v16, v8, v16, s37
	global_store_short_d16_hi v[14:15], v16, off
	v_bfe_u32 v16, v9, 16, 1
	v_add3_u32 v16, v9, v16, s37
	v_lshl_add_u64 v[14:15], v[14:15], 0, v[12:13]
	global_store_short_d16_hi v[14:15], v16, off
	s_and_saveexec_b64 s[10:11], s[40:41]
	s_cbranch_execz .LBB0_497
	v_add_co_u32_e32 v16, vcc, 0x40000, v10
	s_nop 1
	v_addc_co_u32_e32 v17, vcc, 0, v11, vcc
	global_store_dwordx4 v[16:17], v[2:5], off offset:96
	global_store_dwordx4 v[16:17], v[6:9], off offset:112
.LBB0_497:
	s_or_b64 exec, exec, s[10:11]
	v_mov_b64_e32 v[2:3], v[98:99]
	v_lshl_add_u64 v[14:15], v[14:15], 0, v[12:13]
	v_mov_b64_e32 v[4:5], v[100:101]
	v_mov_b64_e32 v[6:7], v[102:103]
	v_mov_b64_e32 v[8:9], v[104:105]
	s_waitcnt lgkmcnt(3)
	v_bfe_u32 v16, v2, 16, 1
	v_add3_u32 v16, v2, v16, s37
	global_store_short_d16_hi v[14:15], v16, off
	v_bfe_u32 v16, v3, 16, 1
	v_add3_u32 v16, v3, v16, s37
	v_lshl_add_u64 v[14:15], v[14:15], 0, v[12:13]
	global_store_short_d16_hi v[14:15], v16, off
	s_waitcnt lgkmcnt(2)
	v_bfe_u32 v16, v4, 16, 1
	v_lshl_add_u64 v[14:15], v[14:15], 0, v[12:13]
	v_add3_u32 v16, v4, v16, s37
	global_store_short_d16_hi v[14:15], v16, off
	v_bfe_u32 v16, v5, 16, 1
	v_add3_u32 v16, v5, v16, s37
	v_lshl_add_u64 v[14:15], v[14:15], 0, v[12:13]
	global_store_short_d16_hi v[14:15], v16, off
	s_waitcnt lgkmcnt(1)
	v_bfe_u32 v16, v6, 16, 1
	v_lshl_add_u64 v[14:15], v[14:15], 0, v[12:13]
	v_add3_u32 v16, v6, v16, s37
	global_store_short_d16_hi v[14:15], v16, off
	v_bfe_u32 v16, v7, 16, 1
	v_add3_u32 v16, v7, v16, s37
	v_lshl_add_u64 v[14:15], v[14:15], 0, v[12:13]
	global_store_short_d16_hi v[14:15], v16, off
	s_waitcnt lgkmcnt(0)
	v_bfe_u32 v16, v8, 16, 1
	v_lshl_add_u64 v[14:15], v[14:15], 0, v[12:13]
	v_add3_u32 v16, v8, v16, s37
	global_store_short_d16_hi v[14:15], v16, off
	v_bfe_u32 v16, v9, 16, 1
	v_add3_u32 v16, v9, v16, s37
	v_lshl_add_u64 v[14:15], v[14:15], 0, v[12:13]
	global_store_short_d16_hi v[14:15], v16, off
	s_and_saveexec_b64 s[10:11], s[40:41]
	s_cbranch_execz .LBB0_499
	v_add_co_u32_e32 v16, vcc, 0x40000, v10
	s_nop 1
	v_addc_co_u32_e32 v17, vcc, 0, v11, vcc
	global_store_dwordx4 v[16:17], v[2:5], off offset:128
	global_store_dwordx4 v[16:17], v[6:9], off offset:144
.LBB0_499:
	s_or_b64 exec, exec, s[10:11]
	v_mov_b64_e32 v[2:3], v[106:107]
	v_lshl_add_u64 v[14:15], v[14:15], 0, v[12:13]
	v_mov_b64_e32 v[4:5], v[108:109]
	v_mov_b64_e32 v[6:7], v[110:111]
	v_mov_b64_e32 v[8:9], v[112:113]
	s_waitcnt lgkmcnt(3)
	v_bfe_u32 v16, v2, 16, 1
	v_add3_u32 v16, v2, v16, s37
	global_store_short_d16_hi v[14:15], v16, off
	v_bfe_u32 v16, v3, 16, 1
	v_add3_u32 v16, v3, v16, s37
	v_lshl_add_u64 v[14:15], v[14:15], 0, v[12:13]
	global_store_short_d16_hi v[14:15], v16, off
	s_waitcnt lgkmcnt(2)
	v_bfe_u32 v16, v4, 16, 1
	v_lshl_add_u64 v[14:15], v[14:15], 0, v[12:13]
	v_add3_u32 v16, v4, v16, s37
	global_store_short_d16_hi v[14:15], v16, off
	v_bfe_u32 v16, v5, 16, 1
	v_add3_u32 v16, v5, v16, s37
	v_lshl_add_u64 v[14:15], v[14:15], 0, v[12:13]
	global_store_short_d16_hi v[14:15], v16, off
	s_waitcnt lgkmcnt(1)
	v_bfe_u32 v16, v6, 16, 1
	v_lshl_add_u64 v[14:15], v[14:15], 0, v[12:13]
	v_add3_u32 v16, v6, v16, s37
	global_store_short_d16_hi v[14:15], v16, off
	v_bfe_u32 v16, v7, 16, 1
	v_add3_u32 v16, v7, v16, s37
	v_lshl_add_u64 v[14:15], v[14:15], 0, v[12:13]
	global_store_short_d16_hi v[14:15], v16, off
	s_waitcnt lgkmcnt(0)
	v_bfe_u32 v16, v8, 16, 1
	v_lshl_add_u64 v[14:15], v[14:15], 0, v[12:13]
	v_add3_u32 v16, v8, v16, s37
	global_store_short_d16_hi v[14:15], v16, off
	v_bfe_u32 v16, v9, 16, 1
	v_add3_u32 v16, v9, v16, s37
	v_lshl_add_u64 v[14:15], v[14:15], 0, v[12:13]
	global_store_short_d16_hi v[14:15], v16, off
	s_and_saveexec_b64 s[10:11], s[40:41]
	s_cbranch_execz .LBB0_501
	v_add_co_u32_e32 v16, vcc, 0x40000, v10
	s_nop 1
	v_addc_co_u32_e32 v17, vcc, 0, v11, vcc
	global_store_dwordx4 v[16:17], v[2:5], off offset:160
	global_store_dwordx4 v[16:17], v[6:9], off offset:176
.LBB0_501:
	s_or_b64 exec, exec, s[10:11]
	v_mov_b64_e32 v[2:3], v[114:115]
	v_lshl_add_u64 v[14:15], v[14:15], 0, v[12:13]
	v_mov_b64_e32 v[4:5], v[116:117]
	v_mov_b64_e32 v[6:7], v[118:119]
	v_mov_b64_e32 v[8:9], v[120:121]
	s_waitcnt lgkmcnt(3)
	v_bfe_u32 v16, v2, 16, 1
	v_add3_u32 v16, v2, v16, s37
	global_store_short_d16_hi v[14:15], v16, off
	v_bfe_u32 v16, v3, 16, 1
	v_add3_u32 v16, v3, v16, s37
	v_lshl_add_u64 v[14:15], v[14:15], 0, v[12:13]
	global_store_short_d16_hi v[14:15], v16, off
	s_waitcnt lgkmcnt(2)
	v_bfe_u32 v16, v4, 16, 1
	v_lshl_add_u64 v[14:15], v[14:15], 0, v[12:13]
	v_add3_u32 v16, v4, v16, s37
	global_store_short_d16_hi v[14:15], v16, off
	v_bfe_u32 v16, v5, 16, 1
	v_add3_u32 v16, v5, v16, s37
	v_lshl_add_u64 v[14:15], v[14:15], 0, v[12:13]
	global_store_short_d16_hi v[14:15], v16, off
	s_waitcnt lgkmcnt(1)
	v_bfe_u32 v16, v6, 16, 1
	v_lshl_add_u64 v[14:15], v[14:15], 0, v[12:13]
	v_add3_u32 v16, v6, v16, s37
	global_store_short_d16_hi v[14:15], v16, off
	v_bfe_u32 v16, v7, 16, 1
	v_add3_u32 v16, v7, v16, s37
	v_lshl_add_u64 v[14:15], v[14:15], 0, v[12:13]
	global_store_short_d16_hi v[14:15], v16, off
	s_waitcnt lgkmcnt(0)
	v_bfe_u32 v16, v8, 16, 1
	v_lshl_add_u64 v[14:15], v[14:15], 0, v[12:13]
	v_add3_u32 v16, v8, v16, s37
	global_store_short_d16_hi v[14:15], v16, off
	v_bfe_u32 v16, v9, 16, 1
	v_add3_u32 v16, v9, v16, s37
	v_lshl_add_u64 v[14:15], v[14:15], 0, v[12:13]
	global_store_short_d16_hi v[14:15], v16, off
	s_and_saveexec_b64 s[10:11], s[40:41]
	s_cbranch_execz .LBB0_503
	v_add_co_u32_e32 v16, vcc, 0x40000, v10
	s_nop 1
	v_addc_co_u32_e32 v17, vcc, 0, v11, vcc
	global_store_dwordx4 v[16:17], v[2:5], off offset:192
	global_store_dwordx4 v[16:17], v[6:9], off offset:208
.LBB0_503:
	s_or_b64 exec, exec, s[10:11]
	v_mov_b64_e32 v[2:3], v[122:123]
	v_lshl_add_u64 v[14:15], v[14:15], 0, v[12:13]
	v_mov_b64_e32 v[4:5], v[124:125]
	v_mov_b64_e32 v[6:7], v[126:127]
	v_mov_b64_e32 v[8:9], v[128:129]
	s_waitcnt lgkmcnt(3)
	v_bfe_u32 v16, v2, 16, 1
	v_add3_u32 v16, v2, v16, s37
	global_store_short_d16_hi v[14:15], v16, off
	v_bfe_u32 v16, v3, 16, 1
	v_add3_u32 v16, v3, v16, s37
	v_lshl_add_u64 v[14:15], v[14:15], 0, v[12:13]
	global_store_short_d16_hi v[14:15], v16, off
	s_waitcnt lgkmcnt(2)
	v_bfe_u32 v16, v4, 16, 1
	v_lshl_add_u64 v[14:15], v[14:15], 0, v[12:13]
	v_add3_u32 v16, v4, v16, s37
	global_store_short_d16_hi v[14:15], v16, off
	v_bfe_u32 v16, v5, 16, 1
	v_add3_u32 v16, v5, v16, s37
	v_lshl_add_u64 v[14:15], v[14:15], 0, v[12:13]
	global_store_short_d16_hi v[14:15], v16, off
	s_waitcnt lgkmcnt(1)
	v_bfe_u32 v16, v6, 16, 1
	v_lshl_add_u64 v[14:15], v[14:15], 0, v[12:13]
	v_add3_u32 v16, v6, v16, s37
	global_store_short_d16_hi v[14:15], v16, off
	v_bfe_u32 v16, v7, 16, 1
	v_add3_u32 v16, v7, v16, s37
	v_lshl_add_u64 v[14:15], v[14:15], 0, v[12:13]
	global_store_short_d16_hi v[14:15], v16, off
	s_waitcnt lgkmcnt(0)
	v_bfe_u32 v16, v8, 16, 1
	v_lshl_add_u64 v[14:15], v[14:15], 0, v[12:13]
	v_add3_u32 v16, v8, v16, s37
	global_store_short_d16_hi v[14:15], v16, off
	v_bfe_u32 v16, v9, 16, 1
	v_add3_u32 v16, v9, v16, s37
	v_lshl_add_u64 v[12:13], v[14:15], 0, v[12:13]
	global_store_short_d16_hi v[12:13], v16, off
	s_and_saveexec_b64 s[10:11], s[40:41]
	s_cbranch_execz .LBB0_505
	v_add_co_u32_e32 v10, vcc, 0x40000, v10
	s_nop 1
	v_addc_co_u32_e32 v11, vcc, 0, v11, vcc
	global_store_dwordx4 v[10:11], v[2:5], off offset:224
	global_store_dwordx4 v[10:11], v[6:9], off offset:240

.LBB0_507:
	s_and_b64 vcc, exec, s[10:11]
	s_cbranch_vccz .LBB0_525
	s_cmp_eq_u32 s19, 3
	v_readlane_b32 s72, v252, 2
	s_cselect_b64 s[10:11], -1, 0
	s_cmp_eq_u32 s19, 2
	v_readlane_b32 s86, v252, 16
	v_readlane_b32 s16, v250, 18
	v_readlane_b32 s87, v252, 17
	v_readlane_b32 s17, v250, 19
	s_cselect_b32 s12, s86, s16
	s_mov_b32 s14, 0xc885100
	s_cselect_b32 s13, s87, s17
	s_cselect_b32 s14, s14, 0xd085100
	s_add_u32 s12, s12, s4
	s_addc_u32 s13, s13, s5
	ds_read2_b32 v[34:35], v155 offset1:1
	ds_read2_b32 v[36:37], v155 offset0:2 offset1:3
	ds_read2_b32 v[38:39], v155 offset0:4 offset1:5
	ds_read2_b32 v[40:41], v155 offset0:6 offset1:7
	ds_read2_b32 v[42:43], v155 offset0:8 offset1:9
	ds_read2_b32 v[44:45], v155 offset0:10 offset1:11
	ds_read2_b32 v[46:47], v155 offset0:12 offset1:13
	ds_read2_b32 v[48:49], v155 offset0:14 offset1:15
	ds_read2_b32 v[50:51], v155 offset0:16 offset1:17
	ds_read2_b32 v[52:53], v155 offset0:18 offset1:19
	ds_read2_b32 v[54:55], v155 offset0:20 offset1:21
	ds_read2_b32 v[56:57], v155 offset0:22 offset1:23
	ds_read2_b32 v[58:59], v155 offset0:24 offset1:25
	ds_read2_b32 v[60:61], v155 offset0:26 offset1:27
	ds_read2_b32 v[62:63], v155 offset0:28 offset1:29
	ds_read2_b32 v[64:65], v155 offset0:30 offset1:31
	ds_read2_b32 v[98:99], v155 offset0:32 offset1:33
	ds_read2_b32 v[100:101], v155 offset0:34 offset1:35
	ds_read2_b32 v[102:103], v155 offset0:36 offset1:37
	ds_read2_b32 v[104:105], v155 offset0:38 offset1:39
	ds_read2_b32 v[106:107], v155 offset0:40 offset1:41
	ds_read2_b32 v[108:109], v155 offset0:42 offset1:43
	ds_read2_b32 v[110:111], v155 offset0:44 offset1:45
	ds_read2_b32 v[112:113], v155 offset0:46 offset1:47
	ds_read2_b32 v[114:115], v155 offset0:48 offset1:49
	ds_read2_b32 v[116:117], v155 offset0:50 offset1:51
	ds_read2_b32 v[118:119], v155 offset0:52 offset1:53
	ds_read2_b32 v[120:121], v155 offset0:54 offset1:55
	ds_read2_b32 v[122:123], v155 offset0:56 offset1:57
	ds_read2_b32 v[124:125], v155 offset0:58 offset1:59
	ds_read2_b32 v[126:127], v155 offset0:60 offset1:61
	ds_read2_b32 v[128:129], v155 offset0:62 offset1:63
	global_load_dwordx4 v[158:161], v1, s[12:13]
	global_load_dwordx4 v[162:165], v1, s[12:13] offset:16
	global_load_dwordx4 v[166:169], v1, s[12:13] offset:32
	global_load_dwordx4 v[170:173], v1, s[12:13] offset:48
	global_load_dwordx4 v[174:177], v1, s[12:13] offset:64
	global_load_dwordx4 v[178:181], v1, s[12:13] offset:80
	global_load_dwordx4 v[182:185], v1, s[12:13] offset:96
	global_load_dwordx4 v[186:189], v1, s[12:13] offset:112
	global_load_dwordx4 v[190:193], v1, s[12:13] offset:128
	global_load_dwordx4 v[194:197], v1, s[12:13] offset:144
	global_load_dwordx4 v[2:5], v1, s[12:13] offset:160
	global_load_dwordx4 v[6:9], v1, s[12:13] offset:176
	global_load_dwordx4 v[10:13], v1, s[12:13] offset:192
	global_load_dwordx4 v[14:17], v1, s[12:13] offset:208
	global_load_dwordx4 v[18:21], v1, s[12:13] offset:224
	global_load_dwordx4 v[28:31], v1, s[12:13] offset:240
	s_add_u32 s14, s94, s14
	v_ashrrev_i32_e32 v27, 31, v26
	s_addc_u32 s15, s95, 0
	v_lshl_add_u64 v[26:27], v[26:27], 4, s[0:1]
	v_lshl_add_u64 v[32:33], v[32:33], 1, s[14:15]
	v_or_b32_e32 v26, v26, v25
	v_readlane_b32 s14, v251, 53
	v_lshlrev_b64 v[26:27], 16, v[26:27]
	v_readlane_b32 s15, v251, 54
	v_lshlrev_b32_e32 v0, 8, v0
	s_and_b64 s[10:11], s[10:11], s[40:41]
	v_lshl_add_u64 v[26:27], s[14:15], 0, v[26:27]
	v_lshl_add_u64 v[26:27], v[26:27], 0, v[0:1]
	v_readlane_b32 s73, v252, 3
	v_readlane_b32 s74, v252, 4
	v_readlane_b32 s75, v252, 5
	v_readlane_b32 s76, v252, 6
	v_readlane_b32 s77, v252, 7
	v_readlane_b32 s78, v252, 8
	v_readlane_b32 s79, v252, 9
	v_readlane_b32 s80, v252, 10
	v_readlane_b32 s81, v252, 11
	v_readlane_b32 s82, v252, 12
	v_readlane_b32 s83, v252, 13
	v_readlane_b32 s84, v252, 14
	v_readlane_b32 s85, v252, 15
	v_readlane_b32 s18, v250, 20
	v_readlane_b32 s19, v250, 21
	v_readlane_b32 s20, v250, 22
	v_readlane_b32 s21, v250, 23
	v_readlane_b32 s22, v250, 24
	v_readlane_b32 s23, v250, 25
	v_readlane_b32 s24, v250, 26
	v_readlane_b32 s25, v250, 27
	v_readlane_b32 s26, v250, 28
	v_readlane_b32 s27, v250, 29
	v_readlane_b32 s28, v250, 30
	v_readlane_b32 s29, v250, 31
	v_readlane_b32 s30, v250, 32
	v_readlane_b32 s31, v250, 33
	s_waitcnt lgkmcnt(15)
	v_pk_mul_f32 v[142:143], v[34:35], v[34:35]
	v_add_f32_e32 v0, v142, v143
	v_pk_mul_f32 v[144:145], v[36:37], v[36:37]
	v_add_f32_e32 v0, v0, v144
	v_add_f32_e32 v0, v0, v145
	v_pk_mul_f32 v[142:143], v[38:39], v[38:39]
	v_add_f32_e32 v0, v0, v142
	v_add_f32_e32 v0, v0, v143
	v_pk_mul_f32 v[144:145], v[40:41], v[40:41]
	v_add_f32_e32 v0, v0, v144
	v_add_f32_e32 v0, v0, v145
	v_pk_mul_f32 v[142:143], v[42:43], v[42:43]
	v_add_f32_e32 v0, v0, v142
	v_add_f32_e32 v0, v0, v143
	v_pk_mul_f32 v[144:145], v[44:45], v[44:45]
	v_add_f32_e32 v0, v0, v144
	v_add_f32_e32 v0, v0, v145
	v_pk_mul_f32 v[142:143], v[46:47], v[46:47]
	v_add_f32_e32 v0, v0, v142
	v_add_f32_e32 v0, v0, v143
	v_pk_mul_f32 v[144:145], v[48:49], v[48:49]
	v_add_f32_e32 v0, v0, v144
	v_add_f32_e32 v0, v0, v145
	v_pk_mul_f32 v[142:143], v[50:51], v[50:51]
	v_add_f32_e32 v0, v0, v142
	v_add_f32_e32 v0, v0, v143
	v_pk_mul_f32 v[144:145], v[52:53], v[52:53]
	v_add_f32_e32 v0, v0, v144
	v_add_f32_e32 v0, v0, v145
	v_pk_mul_f32 v[142:143], v[54:55], v[54:55]
	v_add_f32_e32 v0, v0, v142
	v_add_f32_e32 v0, v0, v143
	v_pk_mul_f32 v[144:145], v[56:57], v[56:57]
	v_add_f32_e32 v0, v0, v144
	v_add_f32_e32 v0, v0, v145
	v_pk_mul_f32 v[142:143], v[58:59], v[58:59]
	v_add_f32_e32 v0, v0, v142
	v_add_f32_e32 v0, v0, v143
	v_pk_mul_f32 v[144:145], v[60:61], v[60:61]
	v_add_f32_e32 v0, v0, v144
	v_add_f32_e32 v0, v0, v145
	v_pk_mul_f32 v[142:143], v[62:63], v[62:63]
	v_add_f32_e32 v0, v0, v142
	v_add_f32_e32 v0, v0, v143
	v_pk_mul_f32 v[144:145], v[64:65], v[64:65]
	v_add_f32_e32 v0, v0, v144
	v_add_f32_e32 v0, v0, v145
	v_pk_mul_f32 v[142:143], v[98:99], v[98:99]
	v_add_f32_e32 v0, v0, v142
	v_add_f32_e32 v0, v0, v143
	s_waitcnt lgkmcnt(14)
	v_pk_mul_f32 v[144:145], v[100:101], v[100:101]
	v_add_f32_e32 v0, v0, v144
	v_add_f32_e32 v0, v0, v145
	s_waitcnt lgkmcnt(13)
	v_pk_mul_f32 v[142:143], v[102:103], v[102:103]
	v_add_f32_e32 v0, v0, v142
	v_add_f32_e32 v0, v0, v143
	s_waitcnt lgkmcnt(12)
	v_pk_mul_f32 v[144:145], v[104:105], v[104:105]
	v_add_f32_e32 v0, v0, v144
	v_add_f32_e32 v0, v0, v145
	s_waitcnt lgkmcnt(11)
	v_pk_mul_f32 v[142:143], v[106:107], v[106:107]
	v_add_f32_e32 v0, v0, v142
	v_add_f32_e32 v0, v0, v143
	s_waitcnt lgkmcnt(10)
	v_pk_mul_f32 v[144:145], v[108:109], v[108:109]
	v_add_f32_e32 v0, v0, v144
	v_add_f32_e32 v0, v0, v145
	s_waitcnt lgkmcnt(9)
	v_pk_mul_f32 v[142:143], v[110:111], v[110:111]
	v_add_f32_e32 v0, v0, v142
	v_add_f32_e32 v0, v0, v143
	s_waitcnt lgkmcnt(8)
	v_pk_mul_f32 v[144:145], v[112:113], v[112:113]
	v_add_f32_e32 v0, v0, v144
	v_add_f32_e32 v0, v0, v145
	s_waitcnt lgkmcnt(7)
	v_pk_mul_f32 v[142:143], v[114:115], v[114:115]
	v_add_f32_e32 v0, v0, v142
	v_add_f32_e32 v0, v0, v143
	s_waitcnt lgkmcnt(6)
	v_pk_mul_f32 v[144:145], v[116:117], v[116:117]
	v_add_f32_e32 v0, v0, v144
	v_add_f32_e32 v0, v0, v145
	s_waitcnt lgkmcnt(5)
	v_pk_mul_f32 v[142:143], v[118:119], v[118:119]
	v_add_f32_e32 v0, v0, v142
	v_add_f32_e32 v0, v0, v143
	s_waitcnt lgkmcnt(4)
	v_pk_mul_f32 v[144:145], v[120:121], v[120:121]
	v_add_f32_e32 v0, v0, v144
	v_add_f32_e32 v0, v0, v145
	s_waitcnt lgkmcnt(3)
	v_pk_mul_f32 v[142:143], v[122:123], v[122:123]
	v_add_f32_e32 v0, v0, v142
	v_add_f32_e32 v0, v0, v143
	s_waitcnt lgkmcnt(2)
	v_pk_mul_f32 v[144:145], v[124:125], v[124:125]
	v_add_f32_e32 v0, v0, v144
	v_add_f32_e32 v0, v0, v145
	s_waitcnt lgkmcnt(1)
	v_pk_mul_f32 v[142:143], v[126:127], v[126:127]
	v_add_f32_e32 v0, v0, v142
	v_add_f32_e32 v0, v0, v143
	s_waitcnt lgkmcnt(0)
	v_pk_mul_f32 v[144:145], v[128:129], v[128:129]
	v_add_f32_e32 v0, v0, v144
	v_add_f32_e32 v0, v0, v145
	v_fmamk_f32 v0, v0, 0x3c800000, v213
	v_cmp_gt_f32_e32 vcc, s54, v0
	v_mul_f32_e32 v22, 0x4b800000, v0
	s_nop 0
	v_cndmask_b32_e32 v0, v0, v22, vcc
	v_rsq_f32_e32 v0, v0
	s_nop 0
	v_mul_f32_e32 v22, 0x45800000, v0
	v_cndmask_b32_e32 v146, v0, v22, vcc
	s_waitcnt vmcnt(0)
	v_pk_mul_f32 v[34:35], v[34:35], v[146:147] op_sel_hi:[1,0]
	v_pk_mul_f32 v[36:37], v[36:37], v[146:147] op_sel_hi:[1,0]
	v_pk_mul_f32 v[38:39], v[38:39], v[146:147] op_sel_hi:[1,0]
	v_pk_mul_f32 v[40:41], v[40:41], v[146:147] op_sel_hi:[1,0]
	v_pk_mul_f32 v[34:35], v[34:35], v[158:159]
	v_pk_mul_f32 v[36:37], v[36:37], v[160:161]
	v_pk_mul_f32 v[38:39], v[38:39], v[162:163]
	v_pk_mul_f32 v[40:41], v[40:41], v[164:165]
	v_cvt_pk_bf16_f32 v158, v34, v35
	v_cvt_pk_bf16_f32 v159, v36, v37
	v_cvt_pk_bf16_f32 v160, v38, v39
	v_cvt_pk_bf16_f32 v161, v40, v41
	global_store_dwordx4 v[32:33], v[158:161], off
	v_pk_mul_f32 v[42:43], v[42:43], v[146:147] op_sel_hi:[1,0]
	v_pk_mul_f32 v[44:45], v[44:45], v[146:147] op_sel_hi:[1,0]
	v_pk_mul_f32 v[46:47], v[46:47], v[146:147] op_sel_hi:[1,0]
	v_pk_mul_f32 v[48:49], v[48:49], v[146:147] op_sel_hi:[1,0]
	v_pk_mul_f32 v[42:43], v[42:43], v[166:167]
	v_pk_mul_f32 v[44:45], v[44:45], v[168:169]
	v_pk_mul_f32 v[46:47], v[46:47], v[170:171]
	v_pk_mul_f32 v[48:49], v[48:49], v[172:173]
	v_cvt_pk_bf16_f32 v166, v42, v43
	v_cvt_pk_bf16_f32 v167, v44, v45
	v_cvt_pk_bf16_f32 v168, v46, v47
	v_cvt_pk_bf16_f32 v169, v48, v49
	global_store_dwordx4 v[32:33], v[166:169], off offset:16
	v_pk_mul_f32 v[50:51], v[50:51], v[146:147] op_sel_hi:[1,0]
	v_pk_mul_f32 v[52:53], v[52:53], v[146:147] op_sel_hi:[1,0]
	v_pk_mul_f32 v[54:55], v[54:55], v[146:147] op_sel_hi:[1,0]
	v_pk_mul_f32 v[56:57], v[56:57], v[146:147] op_sel_hi:[1,0]
	v_pk_mul_f32 v[50:51], v[50:51], v[174:175]
	v_pk_mul_f32 v[52:53], v[52:53], v[176:177]
	v_pk_mul_f32 v[54:55], v[54:55], v[178:179]
	v_pk_mul_f32 v[56:57], v[56:57], v[180:181]
	v_cvt_pk_bf16_f32 v174, v50, v51
	v_cvt_pk_bf16_f32 v175, v52, v53
	v_cvt_pk_bf16_f32 v176, v54, v55
	v_cvt_pk_bf16_f32 v177, v56, v57
	global_store_dwordx4 v[32:33], v[174:177], off offset:32
	v_pk_mul_f32 v[58:59], v[58:59], v[146:147] op_sel_hi:[1,0]
	v_pk_mul_f32 v[60:61], v[60:61], v[146:147] op_sel_hi:[1,0]
	v_pk_mul_f32 v[62:63], v[62:63], v[146:147] op_sel_hi:[1,0]
	v_pk_mul_f32 v[64:65], v[64:65], v[146:147] op_sel_hi:[1,0]
	v_pk_mul_f32 v[58:59], v[58:59], v[182:183]
	v_pk_mul_f32 v[60:61], v[60:61], v[184:185]
	v_pk_mul_f32 v[62:63], v[62:63], v[186:187]
	v_pk_mul_f32 v[64:65], v[64:65], v[188:189]
	v_cvt_pk_bf16_f32 v182, v58, v59
	v_cvt_pk_bf16_f32 v183, v60, v61
	v_cvt_pk_bf16_f32 v184, v62, v63
	v_cvt_pk_bf16_f32 v185, v64, v65
	global_store_dwordx4 v[32:33], v[182:185], off offset:48
	v_pk_mul_f32 v[98:99], v[98:99], v[146:147] op_sel_hi:[1,0]
	v_pk_mul_f32 v[100:101], v[100:101], v[146:147] op_sel_hi:[1,0]
	v_pk_mul_f32 v[102:103], v[102:103], v[146:147] op_sel_hi:[1,0]
	v_pk_mul_f32 v[104:105], v[104:105], v[146:147] op_sel_hi:[1,0]
	v_pk_mul_f32 v[98:99], v[98:99], v[190:191]
	v_pk_mul_f32 v[100:101], v[100:101], v[192:193]
	v_pk_mul_f32 v[102:103], v[102:103], v[194:195]
	v_pk_mul_f32 v[104:105], v[104:105], v[196:197]
	v_cvt_pk_bf16_f32 v190, v98, v99
	v_cvt_pk_bf16_f32 v191, v100, v101
	v_cvt_pk_bf16_f32 v192, v102, v103
	v_cvt_pk_bf16_f32 v193, v104, v105
	global_store_dwordx4 v[32:33], v[190:193], off offset:64
	v_pk_mul_f32 v[106:107], v[106:107], v[146:147] op_sel_hi:[1,0]
	v_pk_mul_f32 v[108:109], v[108:109], v[146:147] op_sel_hi:[1,0]
	v_pk_mul_f32 v[110:111], v[110:111], v[146:147] op_sel_hi:[1,0]
	v_pk_mul_f32 v[112:113], v[112:113], v[146:147] op_sel_hi:[1,0]
	v_pk_mul_f32 v[106:107], v[106:107], v[2:3]
	v_pk_mul_f32 v[108:109], v[108:109], v[4:5]
	v_pk_mul_f32 v[110:111], v[110:111], v[6:7]
	v_pk_mul_f32 v[112:113], v[112:113], v[8:9]
	v_cvt_pk_bf16_f32 v2, v106, v107
	v_cvt_pk_bf16_f32 v3, v108, v109
	v_cvt_pk_bf16_f32 v4, v110, v111
	v_cvt_pk_bf16_f32 v5, v112, v113
	global_store_dwordx4 v[32:33], v[2:5], off offset:80
	v_pk_mul_f32 v[114:115], v[114:115], v[146:147] op_sel_hi:[1,0]
	v_pk_mul_f32 v[116:117], v[116:117], v[146:147] op_sel_hi:[1,0]
	v_pk_mul_f32 v[118:119], v[118:119], v[146:147] op_sel_hi:[1,0]
	v_pk_mul_f32 v[120:121], v[120:121], v[146:147] op_sel_hi:[1,0]
	v_pk_mul_f32 v[114:115], v[114:115], v[10:11]
	v_pk_mul_f32 v[116:117], v[116:117], v[12:13]
	v_pk_mul_f32 v[118:119], v[118:119], v[14:15]
	v_pk_mul_f32 v[120:121], v[120:121], v[16:17]
	v_cvt_pk_bf16_f32 v10, v114, v115
	v_cvt_pk_bf16_f32 v11, v116, v117
	v_cvt_pk_bf16_f32 v12, v118, v119
	v_cvt_pk_bf16_f32 v13, v120, v121
	global_store_dwordx4 v[32:33], v[10:13], off offset:96
	v_pk_mul_f32 v[122:123], v[122:123], v[146:147] op_sel_hi:[1,0]
	v_pk_mul_f32 v[124:125], v[124:125], v[146:147] op_sel_hi:[1,0]
	v_pk_mul_f32 v[126:127], v[126:127], v[146:147] op_sel_hi:[1,0]
	v_pk_mul_f32 v[128:129], v[128:129], v[146:147] op_sel_hi:[1,0]
	v_pk_mul_f32 v[122:123], v[122:123], v[18:19]
	v_pk_mul_f32 v[124:125], v[124:125], v[20:21]
	v_pk_mul_f32 v[126:127], v[126:127], v[28:29]
	v_pk_mul_f32 v[128:129], v[128:129], v[30:31]
	v_cvt_pk_bf16_f32 v18, v122, v123
	v_cvt_pk_bf16_f32 v19, v124, v125
	v_cvt_pk_bf16_f32 v20, v126, v127
	v_cvt_pk_bf16_f32 v21, v128, v129
	global_store_dwordx4 v[32:33], v[18:21], off offset:112
	s_and_saveexec_b64 s[14:15], s[10:11]
	s_cbranch_execz .Lpje_d_skip
	global_store_dwordx4 v[26:27], v[34:37], off
	global_store_dwordx4 v[26:27], v[38:41], off offset:16
	global_store_dwordx4 v[26:27], v[42:45], off offset:32
	global_store_dwordx4 v[26:27], v[46:49], off offset:48
	global_store_dwordx4 v[26:27], v[50:53], off offset:64
	global_store_dwordx4 v[26:27], v[54:57], off offset:80
	global_store_dwordx4 v[26:27], v[58:61], off offset:96
	global_store_dwordx4 v[26:27], v[62:65], off offset:112
	global_store_dwordx4 v[26:27], v[98:101], off offset:128
	global_store_dwordx4 v[26:27], v[102:105], off offset:144
	global_store_dwordx4 v[26:27], v[106:109], off offset:160
	global_store_dwordx4 v[26:27], v[110:113], off offset:176
	global_store_dwordx4 v[26:27], v[114:117], off offset:192
	global_store_dwordx4 v[26:27], v[118:121], off offset:208
	global_store_dwordx4 v[26:27], v[122:125], off offset:224
	global_store_dwordx4 v[26:27], v[126:129], off offset:240
.Lpje_d_skip:
	s_or_b64 exec, exec, s[14:15]
.LBB0_525:
	s_branch .LBB0_444
.LBB0_526:
	s_and_b64 s[8:9], s[8:9], exec
	s_mov_b32 s8, 0xb885100
	s_cselect_b32 s8, s8, 0xc085100
	s_add_u32 s8, s94, s8
	v_ashrrev_i32_e32 v25, 31, v24
	s_addc_u32 s9, s95, 0
	v_lshlrev_b64 v[2:3], 9, v[24:25]
	v_lshl_add_u64 v[2:3], s[8:9], 0, v[2:3]
	v_lshlrev_b32_e32 v0, 1, v156
	v_lshl_add_u64 v[6:7], v[2:3], 0, v[0:1]
	ds_read2_b32 v[34:35], v155 offset1:1
	ds_read2_b32 v[36:37], v155 offset0:2 offset1:3
	ds_read2_b32 v[38:39], v155 offset0:4 offset1:5
	ds_read2_b32 v[40:41], v155 offset0:6 offset1:7
	ds_read2_b32 v[42:43], v155 offset0:8 offset1:9
	ds_read2_b32 v[44:45], v155 offset0:10 offset1:11
	ds_read2_b32 v[46:47], v155 offset0:12 offset1:13
	ds_read2_b32 v[48:49], v155 offset0:14 offset1:15
	ds_read2_b32 v[50:51], v155 offset0:16 offset1:17
	ds_read2_b32 v[52:53], v155 offset0:18 offset1:19
	ds_read2_b32 v[54:55], v155 offset0:20 offset1:21
	ds_read2_b32 v[56:57], v155 offset0:22 offset1:23
	ds_read2_b32 v[58:59], v155 offset0:24 offset1:25
	ds_read2_b32 v[60:61], v155 offset0:26 offset1:27
	ds_read2_b32 v[62:63], v155 offset0:28 offset1:29
	ds_read2_b32 v[64:65], v155 offset0:30 offset1:31
	ds_read2_b32 v[98:99], v155 offset0:32 offset1:33
	ds_read2_b32 v[100:101], v155 offset0:34 offset1:35
	ds_read2_b32 v[102:103], v155 offset0:36 offset1:37
	ds_read2_b32 v[104:105], v155 offset0:38 offset1:39
	ds_read2_b32 v[106:107], v155 offset0:40 offset1:41
	ds_read2_b32 v[108:109], v155 offset0:42 offset1:43
	ds_read2_b32 v[110:111], v155 offset0:44 offset1:45
	ds_read2_b32 v[112:113], v155 offset0:46 offset1:47
	ds_read2_b32 v[114:115], v155 offset0:48 offset1:49
	ds_read2_b32 v[116:117], v155 offset0:50 offset1:51
	ds_read2_b32 v[118:119], v155 offset0:52 offset1:53
	ds_read2_b32 v[120:121], v155 offset0:54 offset1:55
	ds_read2_b32 v[122:123], v155 offset0:56 offset1:57
	ds_read2_b32 v[124:125], v155 offset0:58 offset1:59
	ds_read2_b32 v[126:127], v155 offset0:60 offset1:61
	ds_read2_b32 v[128:129], v155 offset0:62 offset1:63
	s_waitcnt lgkmcnt(15)
	v_cvt_pk_bf16_f32 v158, v34, v35
	v_cvt_pk_bf16_f32 v159, v36, v37
	v_cvt_pk_bf16_f32 v160, v38, v39
	v_cvt_pk_bf16_f32 v161, v40, v41
	global_store_dwordx4 v[6:7], v[158:161], off
	v_cvt_pk_bf16_f32 v162, v42, v43
	v_cvt_pk_bf16_f32 v163, v44, v45
	v_cvt_pk_bf16_f32 v164, v46, v47
	v_cvt_pk_bf16_f32 v165, v48, v49
	global_store_dwordx4 v[6:7], v[162:165], off offset:16
	v_cvt_pk_bf16_f32 v166, v50, v51
	v_cvt_pk_bf16_f32 v167, v52, v53
	v_cvt_pk_bf16_f32 v168, v54, v55
	v_cvt_pk_bf16_f32 v169, v56, v57
	global_store_dwordx4 v[6:7], v[166:169], off offset:32
	v_cvt_pk_bf16_f32 v170, v58, v59
	v_cvt_pk_bf16_f32 v171, v60, v61
	v_cvt_pk_bf16_f32 v172, v62, v63
	v_cvt_pk_bf16_f32 v173, v64, v65
	global_store_dwordx4 v[6:7], v[170:173], off offset:48
	s_waitcnt lgkmcnt(12)
	v_cvt_pk_bf16_f32 v174, v98, v99
	v_cvt_pk_bf16_f32 v175, v100, v101
	v_cvt_pk_bf16_f32 v176, v102, v103
	v_cvt_pk_bf16_f32 v177, v104, v105
	global_store_dwordx4 v[6:7], v[174:177], off offset:64
	s_waitcnt lgkmcnt(8)
	v_cvt_pk_bf16_f32 v178, v106, v107
	v_cvt_pk_bf16_f32 v179, v108, v109
	v_cvt_pk_bf16_f32 v180, v110, v111
	v_cvt_pk_bf16_f32 v181, v112, v113
	global_store_dwordx4 v[6:7], v[178:181], off offset:80
	s_waitcnt lgkmcnt(4)
	v_cvt_pk_bf16_f32 v182, v114, v115
	v_cvt_pk_bf16_f32 v183, v116, v117
	v_cvt_pk_bf16_f32 v184, v118, v119
	v_cvt_pk_bf16_f32 v185, v120, v121
	global_store_dwordx4 v[6:7], v[182:185], off offset:96
	s_waitcnt lgkmcnt(0)
	v_cvt_pk_bf16_f32 v186, v122, v123
	v_cvt_pk_bf16_f32 v187, v124, v125
	v_cvt_pk_bf16_f32 v188, v126, v127
	v_cvt_pk_bf16_f32 v189, v128, v129
	global_store_dwordx4 v[6:7], v[186:189], off offset:112
	s_branch .LBB0_444
